# v26 with the 16 SwiGLU activation stores hinted sc1 nt (write-through plus streaming) instead of sc1 alone
# baseline (speedup 1.0000x reference)
; __device__ __forceinline__ unsigned cvtpk(float lo, float hi) { f32x2_t v = {lo, hi}; bf16x2_t b = __builtin_convertvector(v, bf16x2_t); return __builtin_bit_cast(unsigned, b); }
; __device__ __forceinline__ float ss_rs(u64 v) { return 1.f / sqrtf((float)v * (SSFI / 1024.f) + 1e-6f); }
;     __device__ __forceinline__ void operator()(const Acc& acc, const Unit& u, int wr, int wc, int fr, int fq) const {
;         const int row0 = u.pm * BM + wr * 64 + fr, col0 = u.pn * 128 + wc * 32 + 8 * fq;
;         u64 sv[2][4];
; #pragma unroll
;         for (int ai = 0; ai < 2; ++ai)
; #pragma unroll
;             for (int m = 0; m < 4; ++m) sv[ai][m] = SS[row0 + ai * HALF + m * 16];
; #pragma unroll
;         for (int ai = 0; ai < 2; ++ai)
; #pragma unroll
;             for (int m = 0; m < 4; ++m) {
;                 const int row = row0 + ai * HALF + m * 16; const float rs = ss_rs(sv[ai][m]);
;                 unsigned w[4];
; #pragma unroll
;                 for (int n = 0; n < 2; ++n) {
;                     const f32x4 gv = acc[ai][0][m][n] * rs, uv = acc[ai][1][m][n] * rs; float h[4];
; #pragma unroll
;                     for (int e = 0; e < 4; ++e) { const float gg = gv[e]; h[e] = gg * __builtin_amdgcn_rcpf(1.f + __builtin_amdgcn_exp2f(-1.4426950408889634f * gg)) * uv[e]; }
;                     w[2 * n] = cvtpk(h[0], h[1]); w[2 * n + 1] = cvtpk(h[2], h[3]);
;                 }
;                 *(u32x4*)(O + (size_t)row * DFF + col0) = (u32x4){w[0], w[1], w[2], w[3]};
.LBB0_84:
	v_lshl_add_u32 v152, s0, 8, v156
	v_ashrrev_i32_e32 v153, 31, v152
	v_lshl_add_u64 v[138:139], v[152:153], 3, s[44:45]
	global_load_dwordx2 v[168:169], v[138:139], off
	global_load_dwordx2 v[150:151], v[138:139], off offset:128
	global_load_dwordx2 v[148:149], v[138:139], off offset:256
	global_load_dwordx2 v[146:147], v[138:139], off offset:384
	v_lshl_or_b32 v154, s1, 7, v158
	v_ashrrev_i32_e32 v155, 31, v154
	global_load_dwordx2 v[144:145], v[138:139], off offset:1024
	global_load_dwordx2 v[142:143], v[138:139], off offset:1152
	global_load_dwordx2 v[140:141], v[138:139], off offset:1280
	v_or_b32_e32 v167, 16, v152
	global_load_dwordx2 v[138:139], v[138:139], off offset:1408
	v_or_b32_e32 v166, 32, v152
	v_or_b32_e32 v165, 48, v152
	v_add_u32_e32 v164, 0x80, v152
	v_add_u32_e32 v163, 0x90, v152
	v_add_u32_e32 v162, 0xa0, v152
	v_add_u32_e32 v153, 0xb0, v152
	s_waitcnt vmcnt(0)
	v_ffbh_u32_e32 v170, v169
	v_min_u32_e32 v170, 32, v170
	v_lshlrev_b64 v[168:169], v170, v[168:169]
	v_min_u32_e32 v168, 1, v168
	v_or_b32_e32 v168, v169, v168
	v_cvt_f32_u32_e32 v168, v168
	v_sub_u32_e32 v169, 32, v170
	v_ldexp_f32 v168, v168, v169
	v_fmamk_f32 v168, v168, 0x2e800000, v226
	v_cmp_gt_f32_e32 vcc, s31, v168
	v_mul_f32_e32 v169, 0x4f800000, v168
	s_nop 0
	v_cndmask_b32_e32 v168, v168, v169, vcc
	v_sqrt_f32_e32 v169, v168
	s_nop 0
	v_add_u32_e32 v170, -1, v169
	v_fma_f32 v171, -v170, v169, v168
	v_cmp_ge_f32_e64 s[42:43], 0, v171
	v_add_u32_e32 v171, 1, v169
	s_nop 0
	v_cndmask_b32_e64 v170, v169, v170, s[42:43]
	v_fma_f32 v169, -v171, v169, v168
	v_cmp_lt_f32_e64 s[42:43], 0, v169
	s_nop 1
	v_cndmask_b32_e64 v169, v170, v171, s[42:43]
	v_mul_f32_e32 v170, 0x37800000, v169
	v_cndmask_b32_e32 v169, v169, v170, vcc
	v_cmp_class_f32_e32 vcc, v168, v227
	s_nop 1
	v_cndmask_b32_e32 v168, v169, v168, vcc
	v_div_scale_f32 v169, s[0:1], v168, v168, 1.0
	v_rcp_f32_e32 v170, v169
	s_nop 0
	v_fma_f32 v171, -v169, v170, 1.0
	v_fmac_f32_e32 v170, v171, v170
	v_div_scale_f32 v171, vcc, 1.0, v168, 1.0
	v_mul_f32_e32 v172, v171, v170
	v_fma_f32 v173, -v169, v172, v171
	v_fmac_f32_e32 v172, v173, v170
	v_fma_f32 v169, -v169, v172, v171
	v_div_fmas_f32 v169, v169, v170, v172
	v_div_fixup_f32 v168, v169, v168, 1.0
	v_pk_mul_f32 v[124:125], v[124:125], v[168:169] op_sel_hi:[1,0]
	s_nop 0
	v_mul_f32_e32 v169, 0xbfb8aa3b, v124
	v_exp_f32_e32 v169, v169
	s_nop 0
	v_add_f32_e32 v169, 1.0, v169
	v_rcp_f32_e32 v170, v169
	v_mul_f32_e32 v169, 0xbfb8aa3b, v125
	v_exp_f32_e32 v169, v169
	s_nop 0
	v_add_f32_e32 v169, 1.0, v169
	v_rcp_f32_e32 v171, v169
	v_pk_mul_f32 v[116:117], v[116:117], v[168:169] op_sel_hi:[1,0]
	v_pk_mul_f32 v[118:119], v[118:119], v[168:169] op_sel_hi:[1,0]
	v_pk_mul_f32 v[112:113], v[112:113], v[168:169] op_sel_hi:[1,0]
	v_pk_mul_f32 v[124:125], v[124:125], v[170:171]
	v_pk_mul_f32 v[114:115], v[114:115], v[168:169] op_sel_hi:[1,0]
	v_pk_mul_f32 v[116:117], v[116:117], v[124:125]
	v_pk_mul_f32 v[124:125], v[126:127], v[168:169] op_sel_hi:[1,0]
	v_cvt_pk_bf16_f32 v116, v116, v117
	v_mul_f32_e32 v126, 0xbfb8aa3b, v124
	v_mul_f32_e32 v127, 0xbfb8aa3b, v125
	v_exp_f32_e32 v126, v126
	v_exp_f32_e32 v127, v127
	v_add_f32_e32 v126, 1.0, v126
	v_add_f32_e32 v127, 1.0, v127
	v_rcp_f32_e32 v126, v126
	v_rcp_f32_e32 v127, v127
	s_nop 0
	v_pk_mul_f32 v[124:125], v[124:125], v[126:127]
	s_nop 0
	v_pk_mul_f32 v[118:119], v[118:119], v[124:125]
	s_nop 0
	v_cvt_pk_bf16_f32 v117, v118, v119
	v_pk_mul_f32 v[118:119], v[120:121], v[168:169] op_sel_hi:[1,0]
	s_nop 0
	v_mul_f32_e32 v120, 0xbfb8aa3b, v118
	v_mul_f32_e32 v121, 0xbfb8aa3b, v119
	v_exp_f32_e32 v120, v120
	v_exp_f32_e32 v121, v121
	v_add_f32_e32 v120, 1.0, v120
	v_add_f32_e32 v121, 1.0, v121
	v_rcp_f32_e32 v120, v120
	v_rcp_f32_e32 v121, v121
	s_nop 0
	v_pk_mul_f32 v[118:119], v[118:119], v[120:121]
	s_nop 0
	v_pk_mul_f32 v[112:113], v[112:113], v[118:119]
	v_pk_mul_f32 v[118:119], v[122:123], v[168:169] op_sel_hi:[1,0]
	s_nop 0
	v_mul_f32_e32 v120, 0xbfb8aa3b, v118
	v_mul_f32_e32 v121, 0xbfb8aa3b, v119
	v_exp_f32_e32 v120, v120
	v_exp_f32_e32 v121, v121
	v_add_f32_e32 v120, 1.0, v120
	v_add_f32_e32 v121, 1.0, v121
	v_rcp_f32_e32 v120, v120
	v_rcp_f32_e32 v121, v121
	s_nop 0
	v_pk_mul_f32 v[118:119], v[118:119], v[120:121]
	s_nop 0
	v_pk_mul_f32 v[114:115], v[114:115], v[118:119]
	v_cvt_pk_bf16_f32 v118, v112, v113
	v_mov_b64_e32 v[112:113], s[36:37]
	v_cvt_pk_bf16_f32 v119, v114, v115
	v_mad_i64_i32 v[120:121], s[0:1], v152, s82, v[112:113]
	v_lshlrev_b64 v[114:115], 1, v[154:155]
	v_lshl_add_u64 v[120:121], v[120:121], 0, v[114:115]
	global_store_dwordx4 v[120:121], v[116:119], off sc1 nt
	s_nop 1
	v_ffbh_u32_e32 v116, v151
	v_min_u32_e32 v118, 32, v116
	v_lshlrev_b64 v[116:117], v118, v[150:151]
	v_min_u32_e32 v116, 1, v116
	v_or_b32_e32 v116, v117, v116
	v_cvt_f32_u32_e32 v116, v116
	v_sub_u32_e32 v117, 32, v118
	v_ldexp_f32 v116, v116, v117
	v_fmamk_f32 v116, v116, 0x2e800000, v226
	v_cmp_gt_f32_e32 vcc, s31, v116
	v_mul_f32_e32 v117, 0x4f800000, v116
	s_nop 0
	v_cndmask_b32_e32 v116, v116, v117, vcc
	v_sqrt_f32_e32 v117, v116
	s_nop 0
	v_add_u32_e32 v118, -1, v117
	v_fma_f32 v119, -v118, v117, v116
	v_cmp_ge_f32_e64 s[42:43], 0, v119
	v_add_u32_e32 v119, 1, v117
	s_nop 0
	v_cndmask_b32_e64 v118, v117, v118, s[42:43]
	v_fma_f32 v117, -v119, v117, v116
	v_cmp_lt_f32_e64 s[42:43], 0, v117
	s_nop 1
	v_cndmask_b32_e64 v117, v118, v119, s[42:43]
	v_mul_f32_e32 v118, 0x37800000, v117
	v_cndmask_b32_e32 v117, v117, v118, vcc
	v_cmp_class_f32_e32 vcc, v116, v227
	s_nop 1
	v_cndmask_b32_e32 v116, v117, v116, vcc
	v_div_scale_f32 v117, s[0:1], v116, v116, 1.0
	v_rcp_f32_e32 v118, v117
	s_nop 0
; __device__ __forceinline__ unsigned cvtpk(float lo, float hi) { f32x2_t v = {lo, hi}; bf16x2_t b = __builtin_convertvector(v, bf16x2_t); return __builtin_bit_cast(unsigned, b); }
; __device__ __forceinline__ float ss_rs(u64 v) { return 1.f / sqrtf((float)v * (SSFI / 1024.f) + 1e-6f); }
;     __device__ __forceinline__ void operator()(const Acc& acc, const Unit& u, int wr, int wc, int fr, int fq) const {
;     ...
;                 const int row = row0 + ai * HALF + m * 16; const float rs = ss_rs(sv[ai][m]);
;                 unsigned w[4];
; #pragma unroll
;                 for (int n = 0; n < 2; ++n) {
;                     const f32x4 gv = acc[ai][0][m][n] * rs, uv = acc[ai][1][m][n] * rs; float h[4];
; #pragma unroll
;                     for (int e = 0; e < 4; ++e) { const float gg = gv[e]; h[e] = gg * __builtin_amdgcn_rcpf(1.f + __builtin_amdgcn_exp2f(-1.4426950408889634f * gg)) * uv[e]; }
;                     w[2 * n] = cvtpk(h[0], h[1]); w[2 * n + 1] = cvtpk(h[2], h[3]);
;                 }
;                 *(u32x4*)(O + (size_t)row * DFF + col0) = (u32x4){w[0], w[1], w[2], w[3]};
	v_fma_f32 v119, -v117, v118, 1.0
	v_fmac_f32_e32 v118, v119, v118
	v_div_scale_f32 v119, vcc, 1.0, v116, 1.0
	v_mul_f32_e32 v120, v119, v118
	v_fma_f32 v121, -v117, v120, v119
	v_fmac_f32_e32 v120, v121, v118
	v_fma_f32 v117, -v117, v120, v119
	v_div_fmas_f32 v117, v117, v118, v120
	v_div_fixup_f32 v116, v117, v116, 1.0
	v_pk_mul_f32 v[108:109], v[108:109], v[116:117] op_sel_hi:[1,0]
	s_nop 0
	v_mul_f32_e32 v117, 0xbfb8aa3b, v108
	v_exp_f32_e32 v117, v117
	s_nop 0
	v_add_f32_e32 v117, 1.0, v117
	v_rcp_f32_e32 v118, v117
	v_mul_f32_e32 v117, 0xbfb8aa3b, v109
	v_exp_f32_e32 v117, v117
	s_nop 0
	v_add_f32_e32 v117, 1.0, v117
	v_rcp_f32_e32 v119, v117
	v_pk_mul_f32 v[104:105], v[104:105], v[116:117] op_sel_hi:[1,0]
	v_pk_mul_f32 v[106:107], v[106:107], v[116:117] op_sel_hi:[1,0]
	v_pk_mul_f32 v[100:101], v[100:101], v[116:117] op_sel_hi:[1,0]
	v_pk_mul_f32 v[108:109], v[108:109], v[118:119]
	v_pk_mul_f32 v[96:97], v[96:97], v[116:117] op_sel_hi:[1,0]
	v_pk_mul_f32 v[104:105], v[104:105], v[108:109]
	v_pk_mul_f32 v[108:109], v[110:111], v[116:117] op_sel_hi:[1,0]
	v_cvt_pk_bf16_f32 v104, v104, v105
	v_mul_f32_e32 v110, 0xbfb8aa3b, v108
	v_mul_f32_e32 v111, 0xbfb8aa3b, v109
	v_exp_f32_e32 v110, v110
	v_exp_f32_e32 v111, v111
	v_pk_mul_f32 v[98:99], v[98:99], v[116:117] op_sel_hi:[1,0]
	v_add_f32_e32 v110, 1.0, v110
	v_add_f32_e32 v111, 1.0, v111
	v_rcp_f32_e32 v110, v110
	v_rcp_f32_e32 v111, v111
	s_nop 0
	v_pk_mul_f32 v[108:109], v[108:109], v[110:111]
	s_nop 0
	v_pk_mul_f32 v[106:107], v[106:107], v[108:109]
	s_nop 0
	v_cvt_pk_bf16_f32 v105, v106, v107
	v_mul_f32_e32 v106, 0xbfb8aa3b, v100
	v_mul_f32_e32 v107, 0xbfb8aa3b, v101
	v_exp_f32_e32 v106, v106
	v_exp_f32_e32 v107, v107
	v_add_f32_e32 v106, 1.0, v106
	v_add_f32_e32 v107, 1.0, v107
	v_rcp_f32_e32 v106, v106
	v_rcp_f32_e32 v107, v107
	s_nop 0
	v_pk_mul_f32 v[100:101], v[100:101], v[106:107]
	s_nop 0
	v_pk_mul_f32 v[96:97], v[96:97], v[100:101]
	v_pk_mul_f32 v[100:101], v[102:103], v[116:117] op_sel_hi:[1,0]
	v_cvt_pk_bf16_f32 v106, v96, v97
	v_mul_f32_e32 v102, 0xbfb8aa3b, v100
	v_mul_f32_e32 v103, 0xbfb8aa3b, v101
	v_exp_f32_e32 v102, v102
	v_exp_f32_e32 v103, v103
	v_mad_i64_i32 v[96:97], s[0:1], v167, s82, v[112:113]
	v_add_f32_e32 v102, 1.0, v102
	v_add_f32_e32 v103, 1.0, v103
	v_rcp_f32_e32 v102, v102
	v_rcp_f32_e32 v103, v103
	v_lshl_add_u64 v[96:97], v[96:97], 0, v[114:115]
	v_pk_mul_f32 v[100:101], v[100:101], v[102:103]
	s_nop 0
	v_pk_mul_f32 v[98:99], v[98:99], v[100:101]
	s_nop 0
	v_cvt_pk_bf16_f32 v107, v98, v99
	global_store_dwordx4 v[96:97], v[104:107], off sc1 nt
	v_ffbh_u32_e32 v96, v149
	v_min_u32_e32 v98, 32, v96
	v_lshlrev_b64 v[96:97], v98, v[148:149]
	v_min_u32_e32 v96, 1, v96
	v_or_b32_e32 v96, v97, v96
	v_cvt_f32_u32_e32 v96, v96
	v_sub_u32_e32 v97, 32, v98
	v_ldexp_f32 v96, v96, v97
	v_fmamk_f32 v96, v96, 0x2e800000, v226
	v_cmp_gt_f32_e32 vcc, s31, v96
	v_mul_f32_e32 v97, 0x4f800000, v96
	s_nop 0
	v_cndmask_b32_e32 v96, v96, v97, vcc
	v_sqrt_f32_e32 v97, v96
	s_nop 0
	v_add_u32_e32 v98, -1, v97
	v_fma_f32 v99, -v98, v97, v96
	v_cmp_ge_f32_e64 s[42:43], 0, v99
	v_add_u32_e32 v99, 1, v97
	s_nop 0
	v_cndmask_b32_e64 v98, v97, v98, s[42:43]
	v_fma_f32 v97, -v99, v97, v96
	v_cmp_lt_f32_e64 s[42:43], 0, v97
	s_nop 1
	v_cndmask_b32_e64 v97, v98, v99, s[42:43]
	v_mul_f32_e32 v98, 0x37800000, v97
	v_cndmask_b32_e32 v97, v97, v98, vcc
	v_cmp_class_f32_e32 vcc, v96, v227
	s_nop 1
	v_cndmask_b32_e32 v96, v97, v96, vcc
	v_div_scale_f32 v97, s[0:1], v96, v96, 1.0
	v_rcp_f32_e32 v98, v97
	s_nop 0
	v_fma_f32 v99, -v97, v98, 1.0
	v_fmac_f32_e32 v98, v99, v98
	v_div_scale_f32 v99, vcc, 1.0, v96, 1.0
	v_mul_f32_e32 v100, v99, v98
	v_fma_f32 v101, -v97, v100, v99
	v_fmac_f32_e32 v100, v101, v98
	v_fma_f32 v97, -v97, v100, v99
	v_div_fmas_f32 v97, v97, v98, v100
	v_div_fixup_f32 v96, v97, v96, 1.0
	v_pk_mul_f32 v[92:93], v[92:93], v[96:97] op_sel_hi:[1,0]
	s_nop 0
	v_mul_f32_e32 v97, 0xbfb8aa3b, v92
	v_exp_f32_e32 v97, v97
	s_nop 0
	v_add_f32_e32 v97, 1.0, v97
	v_rcp_f32_e32 v98, v97
	v_mul_f32_e32 v97, 0xbfb8aa3b, v93
	v_exp_f32_e32 v97, v97
	s_nop 0
	v_add_f32_e32 v97, 1.0, v97
	v_rcp_f32_e32 v99, v97
	v_pk_mul_f32 v[88:89], v[88:89], v[96:97] op_sel_hi:[1,0]
	v_pk_mul_f32 v[90:91], v[90:91], v[96:97] op_sel_hi:[1,0]
	v_pk_mul_f32 v[84:85], v[84:85], v[96:97] op_sel_hi:[1,0]
	v_pk_mul_f32 v[92:93], v[92:93], v[98:99]
	v_pk_mul_f32 v[80:81], v[80:81], v[96:97] op_sel_hi:[1,0]
	v_pk_mul_f32 v[88:89], v[88:89], v[92:93]
	v_pk_mul_f32 v[92:93], v[94:95], v[96:97] op_sel_hi:[1,0]
	v_cvt_pk_bf16_f32 v88, v88, v89
	v_mul_f32_e32 v94, 0xbfb8aa3b, v92
	v_mul_f32_e32 v95, 0xbfb8aa3b, v93
	v_exp_f32_e32 v94, v94
	v_exp_f32_e32 v95, v95
	v_pk_mul_f32 v[82:83], v[82:83], v[96:97] op_sel_hi:[1,0]
	v_add_f32_e32 v94, 1.0, v94
	v_add_f32_e32 v95, 1.0, v95
	v_rcp_f32_e32 v94, v94
	v_rcp_f32_e32 v95, v95
	s_nop 0
	v_pk_mul_f32 v[92:93], v[92:93], v[94:95]
	s_nop 0
	v_pk_mul_f32 v[90:91], v[90:91], v[92:93]
	s_nop 0
	v_cvt_pk_bf16_f32 v89, v90, v91
	v_mul_f32_e32 v90, 0xbfb8aa3b, v84
	v_mul_f32_e32 v91, 0xbfb8aa3b, v85
	v_exp_f32_e32 v90, v90
	v_exp_f32_e32 v91, v91
	v_add_f32_e32 v90, 1.0, v90
	v_add_f32_e32 v91, 1.0, v91
	v_rcp_f32_e32 v90, v90
	v_rcp_f32_e32 v91, v91
	s_nop 0
	v_pk_mul_f32 v[84:85], v[84:85], v[90:91]
	s_nop 0
	v_pk_mul_f32 v[80:81], v[80:81], v[84:85]
	v_pk_mul_f32 v[84:85], v[86:87], v[96:97] op_sel_hi:[1,0]
	v_cvt_pk_bf16_f32 v90, v80, v81
	v_mul_f32_e32 v86, 0xbfb8aa3b, v84
	v_mul_f32_e32 v87, 0xbfb8aa3b, v85
	v_exp_f32_e32 v86, v86
	v_exp_f32_e32 v87, v87
	v_mad_i64_i32 v[80:81], s[0:1], v166, s82, v[112:113]
	v_add_f32_e32 v86, 1.0, v86
	v_add_f32_e32 v87, 1.0, v87
; __device__ __forceinline__ unsigned cvtpk(float lo, float hi) { f32x2_t v = {lo, hi}; bf16x2_t b = __builtin_convertvector(v, bf16x2_t); return __builtin_bit_cast(unsigned, b); }
; __device__ __forceinline__ float ss_rs(u64 v) { return 1.f / sqrtf((float)v * (SSFI / 1024.f) + 1e-6f); }
;     __device__ __forceinline__ void operator()(const Acc& acc, const Unit& u, int wr, int wc, int fr, int fq) const {
;     ...
;                 const int row = row0 + ai * HALF + m * 16; const float rs = ss_rs(sv[ai][m]);
;                 unsigned w[4];
; #pragma unroll
;                 for (int n = 0; n < 2; ++n) {
;                     const f32x4 gv = acc[ai][0][m][n] * rs, uv = acc[ai][1][m][n] * rs; float h[4];
; #pragma unroll
;                     for (int e = 0; e < 4; ++e) { const float gg = gv[e]; h[e] = gg * __builtin_amdgcn_rcpf(1.f + __builtin_amdgcn_exp2f(-1.4426950408889634f * gg)) * uv[e]; }
;                     w[2 * n] = cvtpk(h[0], h[1]); w[2 * n + 1] = cvtpk(h[2], h[3]);
;                 }
;                 *(u32x4*)(O + (size_t)row * DFF + col0) = (u32x4){w[0], w[1], w[2], w[3]};
	v_rcp_f32_e32 v86, v86
	v_rcp_f32_e32 v87, v87
	v_lshl_add_u64 v[80:81], v[80:81], 0, v[114:115]
	v_pk_mul_f32 v[84:85], v[84:85], v[86:87]
	s_nop 0
	v_pk_mul_f32 v[82:83], v[82:83], v[84:85]
	s_nop 0
	v_cvt_pk_bf16_f32 v91, v82, v83
	global_store_dwordx4 v[80:81], v[88:91], off sc1 nt
	v_ffbh_u32_e32 v80, v147
	v_min_u32_e32 v82, 32, v80
	v_lshlrev_b64 v[80:81], v82, v[146:147]
	v_min_u32_e32 v80, 1, v80
	v_or_b32_e32 v80, v81, v80
	v_cvt_f32_u32_e32 v80, v80
	v_sub_u32_e32 v81, 32, v82
	v_ldexp_f32 v80, v80, v81
	v_fmamk_f32 v80, v80, 0x2e800000, v226
	v_cmp_gt_f32_e32 vcc, s31, v80
	v_mul_f32_e32 v81, 0x4f800000, v80
	s_nop 0
	v_cndmask_b32_e32 v80, v80, v81, vcc
	v_sqrt_f32_e32 v81, v80
	s_nop 0
	v_add_u32_e32 v82, -1, v81
	v_fma_f32 v83, -v82, v81, v80
	v_cmp_ge_f32_e64 s[42:43], 0, v83
	v_add_u32_e32 v83, 1, v81
	s_nop 0
	v_cndmask_b32_e64 v82, v81, v82, s[42:43]
	v_fma_f32 v81, -v83, v81, v80
	v_cmp_lt_f32_e64 s[42:43], 0, v81
	s_nop 1
	v_cndmask_b32_e64 v81, v82, v83, s[42:43]
	v_mul_f32_e32 v82, 0x37800000, v81
	v_cndmask_b32_e32 v81, v81, v82, vcc
	v_cmp_class_f32_e32 vcc, v80, v227
	s_nop 1
	v_cndmask_b32_e32 v80, v81, v80, vcc
	v_div_scale_f32 v81, s[0:1], v80, v80, 1.0
	v_rcp_f32_e32 v82, v81
	s_nop 0
	v_fma_f32 v83, -v81, v82, 1.0
	v_fmac_f32_e32 v82, v83, v82
	v_div_scale_f32 v83, vcc, 1.0, v80, 1.0
	v_mul_f32_e32 v84, v83, v82
	v_fma_f32 v85, -v81, v84, v83
	v_fmac_f32_e32 v84, v85, v82
	v_fma_f32 v81, -v81, v84, v83
	v_div_fmas_f32 v81, v81, v82, v84
	v_div_fixup_f32 v80, v81, v80, 1.0
	v_pk_mul_f32 v[76:77], v[76:77], v[80:81] op_sel_hi:[1,0]
	s_nop 0
	v_mul_f32_e32 v81, 0xbfb8aa3b, v76
	v_exp_f32_e32 v81, v81
	s_nop 0
	v_add_f32_e32 v81, 1.0, v81
	v_rcp_f32_e32 v82, v81
	v_mul_f32_e32 v81, 0xbfb8aa3b, v77
	v_exp_f32_e32 v81, v81
	s_nop 0
	v_add_f32_e32 v81, 1.0, v81
	v_rcp_f32_e32 v83, v81
	v_pk_mul_f32 v[72:73], v[72:73], v[80:81] op_sel_hi:[1,0]
	v_pk_mul_f32 v[74:75], v[74:75], v[80:81] op_sel_hi:[1,0]
	v_pk_mul_f32 v[68:69], v[68:69], v[80:81] op_sel_hi:[1,0]
	v_pk_mul_f32 v[76:77], v[76:77], v[82:83]
	v_pk_mul_f32 v[64:65], v[64:65], v[80:81] op_sel_hi:[1,0]
	v_pk_mul_f32 v[72:73], v[72:73], v[76:77]
	v_pk_mul_f32 v[76:77], v[78:79], v[80:81] op_sel_hi:[1,0]
	v_cvt_pk_bf16_f32 v72, v72, v73
	v_mul_f32_e32 v78, 0xbfb8aa3b, v76
	v_mul_f32_e32 v79, 0xbfb8aa3b, v77
	v_exp_f32_e32 v78, v78
	v_exp_f32_e32 v79, v79
	v_pk_mul_f32 v[66:67], v[66:67], v[80:81] op_sel_hi:[1,0]
	v_add_f32_e32 v78, 1.0, v78
	v_add_f32_e32 v79, 1.0, v79
	v_rcp_f32_e32 v78, v78
	v_rcp_f32_e32 v79, v79
	s_nop 0
	v_pk_mul_f32 v[76:77], v[76:77], v[78:79]
	s_nop 0
	v_pk_mul_f32 v[74:75], v[74:75], v[76:77]
	s_nop 0
	v_cvt_pk_bf16_f32 v73, v74, v75
	v_mul_f32_e32 v74, 0xbfb8aa3b, v68
	v_mul_f32_e32 v75, 0xbfb8aa3b, v69
	v_exp_f32_e32 v74, v74
	v_exp_f32_e32 v75, v75
	v_add_f32_e32 v74, 1.0, v74
	v_add_f32_e32 v75, 1.0, v75
	v_rcp_f32_e32 v74, v74
	v_rcp_f32_e32 v75, v75
	s_nop 0
	v_pk_mul_f32 v[68:69], v[68:69], v[74:75]
	s_nop 0
	v_pk_mul_f32 v[64:65], v[64:65], v[68:69]
	v_pk_mul_f32 v[68:69], v[70:71], v[80:81] op_sel_hi:[1,0]
	v_cvt_pk_bf16_f32 v74, v64, v65
	v_mul_f32_e32 v70, 0xbfb8aa3b, v68
	v_mul_f32_e32 v71, 0xbfb8aa3b, v69
	v_exp_f32_e32 v70, v70
	v_exp_f32_e32 v71, v71
	v_mad_i64_i32 v[64:65], s[0:1], v165, s82, v[112:113]
	v_add_f32_e32 v70, 1.0, v70
	v_add_f32_e32 v71, 1.0, v71
	v_rcp_f32_e32 v70, v70
	v_rcp_f32_e32 v71, v71
	v_lshl_add_u64 v[64:65], v[64:65], 0, v[114:115]
	v_pk_mul_f32 v[68:69], v[68:69], v[70:71]
	s_nop 0
	v_pk_mul_f32 v[66:67], v[66:67], v[68:69]
	s_nop 0
	v_cvt_pk_bf16_f32 v75, v66, v67
	global_store_dwordx4 v[64:65], v[72:75], off sc1 nt
	v_ffbh_u32_e32 v64, v145
	v_min_u32_e32 v66, 32, v64
	v_lshlrev_b64 v[64:65], v66, v[144:145]
	v_min_u32_e32 v64, 1, v64
	v_or_b32_e32 v64, v65, v64
	v_cvt_f32_u32_e32 v64, v64
	v_sub_u32_e32 v65, 32, v66
	v_ldexp_f32 v64, v64, v65
	v_fmamk_f32 v64, v64, 0x2e800000, v226
	v_cmp_gt_f32_e32 vcc, s31, v64
	v_mul_f32_e32 v65, 0x4f800000, v64
	s_nop 0
	v_cndmask_b32_e32 v64, v64, v65, vcc
	v_sqrt_f32_e32 v65, v64
	s_nop 0
	v_add_u32_e32 v66, -1, v65
	v_fma_f32 v67, -v66, v65, v64
	v_cmp_ge_f32_e64 s[42:43], 0, v67
	v_add_u32_e32 v67, 1, v65
	s_nop 0
	v_cndmask_b32_e64 v66, v65, v66, s[42:43]
	v_fma_f32 v65, -v67, v65, v64
	v_cmp_lt_f32_e64 s[42:43], 0, v65
	s_nop 1
	v_cndmask_b32_e64 v65, v66, v67, s[42:43]
	v_mul_f32_e32 v66, 0x37800000, v65
	v_cndmask_b32_e32 v65, v65, v66, vcc
	v_cmp_class_f32_e32 vcc, v64, v227
	s_nop 1
	v_cndmask_b32_e32 v64, v65, v64, vcc
	v_div_scale_f32 v65, s[0:1], v64, v64, 1.0
	v_rcp_f32_e32 v66, v65
	s_nop 0
	v_fma_f32 v67, -v65, v66, 1.0
	v_fmac_f32_e32 v66, v67, v66
	v_div_scale_f32 v67, vcc, 1.0, v64, 1.0
	v_mul_f32_e32 v68, v67, v66
	v_fma_f32 v69, -v65, v68, v67
	v_fmac_f32_e32 v68, v69, v66
	v_fma_f32 v65, -v65, v68, v67
	v_div_fmas_f32 v65, v65, v66, v68
	v_div_fixup_f32 v64, v65, v64, 1.0
	v_pk_mul_f32 v[60:61], v[60:61], v[64:65] op_sel_hi:[1,0]
	s_nop 0
	v_mul_f32_e32 v65, 0xbfb8aa3b, v60
	v_exp_f32_e32 v65, v65
	s_nop 0
	v_add_f32_e32 v65, 1.0, v65
	v_rcp_f32_e32 v66, v65
	v_mul_f32_e32 v65, 0xbfb8aa3b, v61
	v_exp_f32_e32 v65, v65
	s_nop 0
	v_add_f32_e32 v65, 1.0, v65
	v_rcp_f32_e32 v67, v65
	v_pk_mul_f32 v[56:57], v[56:57], v[64:65] op_sel_hi:[1,0]
	v_pk_mul_f32 v[58:59], v[58:59], v[64:65] op_sel_hi:[1,0]
	v_pk_mul_f32 v[52:53], v[52:53], v[64:65] op_sel_hi:[1,0]
	v_pk_mul_f32 v[60:61], v[60:61], v[66:67]
	v_pk_mul_f32 v[48:49], v[48:49], v[64:65] op_sel_hi:[1,0]
	v_pk_mul_f32 v[56:57], v[56:57], v[60:61]
	v_pk_mul_f32 v[60:61], v[62:63], v[64:65] op_sel_hi:[1,0]
	v_cvt_pk_bf16_f32 v56, v56, v57
	v_mul_f32_e32 v62, 0xbfb8aa3b, v60
; __device__ __forceinline__ unsigned cvtpk(float lo, float hi) { f32x2_t v = {lo, hi}; bf16x2_t b = __builtin_convertvector(v, bf16x2_t); return __builtin_bit_cast(unsigned, b); }
; __device__ __forceinline__ float ss_rs(u64 v) { return 1.f / sqrtf((float)v * (SSFI / 1024.f) + 1e-6f); }
;     __device__ __forceinline__ void operator()(const Acc& acc, const Unit& u, int wr, int wc, int fr, int fq) const {
;     ...
;                 const int row = row0 + ai * HALF + m * 16; const float rs = ss_rs(sv[ai][m]);
;                 unsigned w[4];
; #pragma unroll
;                 for (int n = 0; n < 2; ++n) {
;                     const f32x4 gv = acc[ai][0][m][n] * rs, uv = acc[ai][1][m][n] * rs; float h[4];
; #pragma unroll
;                     for (int e = 0; e < 4; ++e) { const float gg = gv[e]; h[e] = gg * __builtin_amdgcn_rcpf(1.f + __builtin_amdgcn_exp2f(-1.4426950408889634f * gg)) * uv[e]; }
;                     w[2 * n] = cvtpk(h[0], h[1]); w[2 * n + 1] = cvtpk(h[2], h[3]);
;                 }
;                 *(u32x4*)(O + (size_t)row * DFF + col0) = (u32x4){w[0], w[1], w[2], w[3]};
	v_mul_f32_e32 v63, 0xbfb8aa3b, v61
	v_exp_f32_e32 v62, v62
	v_exp_f32_e32 v63, v63
	v_pk_mul_f32 v[50:51], v[50:51], v[64:65] op_sel_hi:[1,0]
	v_add_f32_e32 v62, 1.0, v62
	v_add_f32_e32 v63, 1.0, v63
	v_rcp_f32_e32 v62, v62
	v_rcp_f32_e32 v63, v63
	s_nop 0
	v_pk_mul_f32 v[60:61], v[60:61], v[62:63]
	s_nop 0
	v_pk_mul_f32 v[58:59], v[58:59], v[60:61]
	s_nop 0
	v_cvt_pk_bf16_f32 v57, v58, v59
	v_mul_f32_e32 v58, 0xbfb8aa3b, v52
	v_mul_f32_e32 v59, 0xbfb8aa3b, v53
	v_exp_f32_e32 v58, v58
	v_exp_f32_e32 v59, v59
	v_add_f32_e32 v58, 1.0, v58
	v_add_f32_e32 v59, 1.0, v59
	v_rcp_f32_e32 v58, v58
	v_rcp_f32_e32 v59, v59
	s_nop 0
	v_pk_mul_f32 v[52:53], v[52:53], v[58:59]
	s_nop 0
	v_pk_mul_f32 v[48:49], v[48:49], v[52:53]
	v_pk_mul_f32 v[52:53], v[54:55], v[64:65] op_sel_hi:[1,0]
	v_cvt_pk_bf16_f32 v58, v48, v49
	v_mul_f32_e32 v54, 0xbfb8aa3b, v52
	v_mul_f32_e32 v55, 0xbfb8aa3b, v53
	v_exp_f32_e32 v54, v54
	v_exp_f32_e32 v55, v55
	v_mad_i64_i32 v[48:49], s[0:1], v164, s82, v[112:113]
	v_add_f32_e32 v54, 1.0, v54
	v_add_f32_e32 v55, 1.0, v55
	v_rcp_f32_e32 v54, v54
	v_rcp_f32_e32 v55, v55
	v_lshl_add_u64 v[48:49], v[48:49], 0, v[114:115]
	v_pk_mul_f32 v[52:53], v[52:53], v[54:55]
	s_nop 0
	v_pk_mul_f32 v[50:51], v[50:51], v[52:53]
	s_nop 0
	v_cvt_pk_bf16_f32 v59, v50, v51
	global_store_dwordx4 v[48:49], v[56:59], off sc1 nt
	v_ffbh_u32_e32 v48, v143
	v_min_u32_e32 v50, 32, v48
	v_lshlrev_b64 v[48:49], v50, v[142:143]
	v_min_u32_e32 v48, 1, v48
	v_or_b32_e32 v48, v49, v48
	v_cvt_f32_u32_e32 v48, v48
	v_sub_u32_e32 v49, 32, v50
	v_ldexp_f32 v48, v48, v49
	v_fmamk_f32 v48, v48, 0x2e800000, v226
	v_cmp_gt_f32_e32 vcc, s31, v48
	v_mul_f32_e32 v49, 0x4f800000, v48
	s_nop 0
	v_cndmask_b32_e32 v48, v48, v49, vcc
	v_sqrt_f32_e32 v49, v48
	s_nop 0
	v_add_u32_e32 v50, -1, v49
	v_fma_f32 v51, -v50, v49, v48
	v_cmp_ge_f32_e64 s[42:43], 0, v51
	v_add_u32_e32 v51, 1, v49
	s_nop 0
	v_cndmask_b32_e64 v50, v49, v50, s[42:43]
	v_fma_f32 v49, -v51, v49, v48
	v_cmp_lt_f32_e64 s[42:43], 0, v49
	s_nop 1
	v_cndmask_b32_e64 v49, v50, v51, s[42:43]
	v_mul_f32_e32 v50, 0x37800000, v49
	v_cndmask_b32_e32 v49, v49, v50, vcc
	v_cmp_class_f32_e32 vcc, v48, v227
	s_nop 1
	v_cndmask_b32_e32 v48, v49, v48, vcc
	v_div_scale_f32 v49, s[0:1], v48, v48, 1.0
	v_rcp_f32_e32 v50, v49
	s_nop 0
	v_fma_f32 v51, -v49, v50, 1.0
	v_fmac_f32_e32 v50, v51, v50
	v_div_scale_f32 v51, vcc, 1.0, v48, 1.0
	v_mul_f32_e32 v52, v51, v50
	v_fma_f32 v53, -v49, v52, v51
	v_fmac_f32_e32 v52, v53, v50
	v_fma_f32 v49, -v49, v52, v51
	v_div_fmas_f32 v49, v49, v50, v52
	v_div_fixup_f32 v48, v49, v48, 1.0
	v_pk_mul_f32 v[44:45], v[44:45], v[48:49] op_sel_hi:[1,0]
	s_nop 0
	v_mul_f32_e32 v49, 0xbfb8aa3b, v44
	v_exp_f32_e32 v49, v49
	s_nop 0
	v_add_f32_e32 v49, 1.0, v49
	v_rcp_f32_e32 v50, v49
	v_mul_f32_e32 v49, 0xbfb8aa3b, v45
	v_exp_f32_e32 v49, v49
	s_nop 0
	v_add_f32_e32 v49, 1.0, v49
	v_rcp_f32_e32 v51, v49
	v_pk_mul_f32 v[40:41], v[40:41], v[48:49] op_sel_hi:[1,0]
	v_pk_mul_f32 v[42:43], v[42:43], v[48:49] op_sel_hi:[1,0]
	v_pk_mul_f32 v[36:37], v[36:37], v[48:49] op_sel_hi:[1,0]
	v_pk_mul_f32 v[44:45], v[44:45], v[50:51]
	v_pk_mul_f32 v[32:33], v[32:33], v[48:49] op_sel_hi:[1,0]
	v_pk_mul_f32 v[40:41], v[40:41], v[44:45]
	v_pk_mul_f32 v[44:45], v[46:47], v[48:49] op_sel_hi:[1,0]
	v_cvt_pk_bf16_f32 v40, v40, v41
	v_mul_f32_e32 v46, 0xbfb8aa3b, v44
	v_mul_f32_e32 v47, 0xbfb8aa3b, v45
	v_exp_f32_e32 v46, v46
	v_exp_f32_e32 v47, v47
	v_pk_mul_f32 v[34:35], v[34:35], v[48:49] op_sel_hi:[1,0]
	v_add_f32_e32 v46, 1.0, v46
	v_add_f32_e32 v47, 1.0, v47
	v_rcp_f32_e32 v46, v46
	v_rcp_f32_e32 v47, v47
	s_nop 0
	v_pk_mul_f32 v[44:45], v[44:45], v[46:47]
	s_nop 0
	v_pk_mul_f32 v[42:43], v[42:43], v[44:45]
	s_nop 0
	v_cvt_pk_bf16_f32 v41, v42, v43
	v_mul_f32_e32 v42, 0xbfb8aa3b, v36
	v_mul_f32_e32 v43, 0xbfb8aa3b, v37
	v_exp_f32_e32 v42, v42
	v_exp_f32_e32 v43, v43
	v_add_f32_e32 v42, 1.0, v42
	v_add_f32_e32 v43, 1.0, v43
	v_rcp_f32_e32 v42, v42
	v_rcp_f32_e32 v43, v43
	s_nop 0
	v_pk_mul_f32 v[36:37], v[36:37], v[42:43]
	s_nop 0
	v_pk_mul_f32 v[32:33], v[32:33], v[36:37]
	v_pk_mul_f32 v[36:37], v[38:39], v[48:49] op_sel_hi:[1,0]
	v_cvt_pk_bf16_f32 v42, v32, v33
	v_mul_f32_e32 v38, 0xbfb8aa3b, v36
	v_mul_f32_e32 v39, 0xbfb8aa3b, v37
	v_exp_f32_e32 v38, v38
	v_exp_f32_e32 v39, v39
	v_mad_i64_i32 v[32:33], s[0:1], v163, s82, v[112:113]
	v_add_f32_e32 v38, 1.0, v38
	v_add_f32_e32 v39, 1.0, v39
	v_rcp_f32_e32 v38, v38
	v_rcp_f32_e32 v39, v39
	v_lshl_add_u64 v[32:33], v[32:33], 0, v[114:115]
	v_pk_mul_f32 v[36:37], v[36:37], v[38:39]
	s_nop 0
	v_pk_mul_f32 v[34:35], v[34:35], v[36:37]
	s_nop 0
	v_cvt_pk_bf16_f32 v43, v34, v35
	global_store_dwordx4 v[32:33], v[40:43], off sc1 nt
	v_ffbh_u32_e32 v32, v141
	v_min_u32_e32 v34, 32, v32
	v_lshlrev_b64 v[32:33], v34, v[140:141]
	v_min_u32_e32 v32, 1, v32
	v_or_b32_e32 v32, v33, v32
	v_cvt_f32_u32_e32 v32, v32
	v_sub_u32_e32 v33, 32, v34
	v_ldexp_f32 v32, v32, v33
	v_fmamk_f32 v32, v32, 0x2e800000, v226
	v_cmp_gt_f32_e32 vcc, s31, v32
	v_mul_f32_e32 v33, 0x4f800000, v32
	s_nop 0
	v_cndmask_b32_e32 v32, v32, v33, vcc
	v_sqrt_f32_e32 v33, v32
	s_nop 0
	v_add_u32_e32 v34, -1, v33
	v_fma_f32 v35, -v34, v33, v32
	v_cmp_ge_f32_e64 s[42:43], 0, v35
	v_add_u32_e32 v35, 1, v33
	s_nop 0
	v_cndmask_b32_e64 v34, v33, v34, s[42:43]
	v_fma_f32 v33, -v35, v33, v32
	v_cmp_lt_f32_e64 s[42:43], 0, v33
	s_nop 1
	v_cndmask_b32_e64 v33, v34, v35, s[42:43]
	v_mul_f32_e32 v34, 0x37800000, v33
	v_cndmask_b32_e32 v33, v33, v34, vcc
	v_cmp_class_f32_e32 vcc, v32, v227
	s_nop 1
	v_cndmask_b32_e32 v32, v33, v32, vcc
	v_div_scale_f32 v33, s[0:1], v32, v32, 1.0
	v_rcp_f32_e32 v34, v33
	s_nop 0
; __device__ __forceinline__ unsigned cvtpk(float lo, float hi) { f32x2_t v = {lo, hi}; bf16x2_t b = __builtin_convertvector(v, bf16x2_t); return __builtin_bit_cast(unsigned, b); }
; __device__ __forceinline__ float ss_rs(u64 v) { return 1.f / sqrtf((float)v * (SSFI / 1024.f) + 1e-6f); }
; #define PG8_BAR __builtin_amdgcn_s_barrier()
; template <class Epi, bool ALIGN_EPI = true>
; __device__ __forceinline__ void gemm_phase(LAS unsigned char* lds, const Gemm g, const StaticOrder& S, const Epi& E, int wave_k) {
;     ...
;         if (!has_next) break;
; #pragma unroll
;         for (int a = 0; a < 2; ++a)
; #pragma unroll
;             for (int b = 0; b < 2; ++b)
; #pragma unroll
;                 for (int m = 0; m < 4; ++m)
; #pragma unroll
;                     for (int n = 0; n < 2; ++n) acc[a][b][m][n] = (f32x4){0.f, 0.f, 0.f, 0.f};
;         cur = nxt; cA = nA; cB = nB; ++ui;
;         if constexpr (ALIGN_EPI) { if (wr == 1) PG8_BAR; }
;     __device__ __forceinline__ void operator()(const Acc& acc, const Unit& u, int wr, int wc, int fr, int fq) const {
;     ...
;                 const int row = row0 + ai * HALF + m * 16; const float rs = ss_rs(sv[ai][m]);
;                 unsigned w[4];
; #pragma unroll
;                 for (int n = 0; n < 2; ++n) {
;                     const f32x4 gv = acc[ai][0][m][n] * rs, uv = acc[ai][1][m][n] * rs; float h[4];
; #pragma unroll
;                     for (int e = 0; e < 4; ++e) { const float gg = gv[e]; h[e] = gg * __builtin_amdgcn_rcpf(1.f + __builtin_amdgcn_exp2f(-1.4426950408889634f * gg)) * uv[e]; }
;                     w[2 * n] = cvtpk(h[0], h[1]); w[2 * n + 1] = cvtpk(h[2], h[3]);
;                 }
;                 *(u32x4*)(O + (size_t)row * DFF + col0) = (u32x4){w[0], w[1], w[2], w[3]};
	v_fma_f32 v35, -v33, v34, 1.0
	v_fmac_f32_e32 v34, v35, v34
	v_div_scale_f32 v35, vcc, 1.0, v32, 1.0
	v_mul_f32_e32 v36, v35, v34
	v_fma_f32 v37, -v33, v36, v35
	v_fmac_f32_e32 v36, v37, v34
	v_fma_f32 v33, -v33, v36, v35
	v_div_fmas_f32 v33, v33, v34, v36
	v_div_fixup_f32 v32, v33, v32, 1.0
	v_pk_mul_f32 v[28:29], v[28:29], v[32:33] op_sel_hi:[1,0]
	s_nop 0
	v_mul_f32_e32 v33, 0xbfb8aa3b, v28
	v_exp_f32_e32 v33, v33
	s_nop 0
	v_add_f32_e32 v33, 1.0, v33
	v_rcp_f32_e32 v34, v33
	v_mul_f32_e32 v33, 0xbfb8aa3b, v29
	v_exp_f32_e32 v33, v33
	s_nop 0
	v_add_f32_e32 v33, 1.0, v33
	v_rcp_f32_e32 v35, v33
	v_pk_mul_f32 v[24:25], v[24:25], v[32:33] op_sel_hi:[1,0]
	v_pk_mul_f32 v[26:27], v[26:27], v[32:33] op_sel_hi:[1,0]
	v_pk_mul_f32 v[20:21], v[20:21], v[32:33] op_sel_hi:[1,0]
	v_pk_mul_f32 v[28:29], v[28:29], v[34:35]
	v_pk_mul_f32 v[16:17], v[16:17], v[32:33] op_sel_hi:[1,0]
	v_pk_mul_f32 v[24:25], v[24:25], v[28:29]
	v_pk_mul_f32 v[28:29], v[30:31], v[32:33] op_sel_hi:[1,0]
	v_cvt_pk_bf16_f32 v24, v24, v25
	v_mul_f32_e32 v30, 0xbfb8aa3b, v28
	v_mul_f32_e32 v31, 0xbfb8aa3b, v29
	v_exp_f32_e32 v30, v30
	v_exp_f32_e32 v31, v31
	v_pk_mul_f32 v[18:19], v[18:19], v[32:33] op_sel_hi:[1,0]
	v_add_f32_e32 v30, 1.0, v30
	v_add_f32_e32 v31, 1.0, v31
	v_rcp_f32_e32 v30, v30
	v_rcp_f32_e32 v31, v31
	s_nop 0
	v_pk_mul_f32 v[28:29], v[28:29], v[30:31]
	s_nop 0
	v_pk_mul_f32 v[26:27], v[26:27], v[28:29]
	s_nop 0
	v_cvt_pk_bf16_f32 v25, v26, v27
	v_mul_f32_e32 v26, 0xbfb8aa3b, v20
	v_mul_f32_e32 v27, 0xbfb8aa3b, v21
	v_exp_f32_e32 v26, v26
	v_exp_f32_e32 v27, v27
	v_add_f32_e32 v26, 1.0, v26
	v_add_f32_e32 v27, 1.0, v27
	v_rcp_f32_e32 v26, v26
	v_rcp_f32_e32 v27, v27
	s_nop 0
	v_pk_mul_f32 v[20:21], v[20:21], v[26:27]
	s_nop 0
	v_pk_mul_f32 v[16:17], v[16:17], v[20:21]
	v_pk_mul_f32 v[20:21], v[22:23], v[32:33] op_sel_hi:[1,0]
	v_cvt_pk_bf16_f32 v26, v16, v17
	v_mul_f32_e32 v22, 0xbfb8aa3b, v20
	v_mul_f32_e32 v23, 0xbfb8aa3b, v21
	v_exp_f32_e32 v22, v22
	v_exp_f32_e32 v23, v23
	v_mad_i64_i32 v[16:17], s[0:1], v162, s82, v[112:113]
	v_add_f32_e32 v22, 1.0, v22
	v_add_f32_e32 v23, 1.0, v23
	v_rcp_f32_e32 v22, v22
	v_rcp_f32_e32 v23, v23
	v_lshl_add_u64 v[16:17], v[16:17], 0, v[114:115]
	v_pk_mul_f32 v[20:21], v[20:21], v[22:23]
	s_nop 0
	v_pk_mul_f32 v[18:19], v[18:19], v[20:21]
	s_nop 0
	v_cvt_pk_bf16_f32 v27, v18, v19
	global_store_dwordx4 v[16:17], v[24:27], off sc1 nt
	v_ffbh_u32_e32 v16, v139
	v_min_u32_e32 v18, 32, v16
	v_lshlrev_b64 v[16:17], v18, v[138:139]
	v_min_u32_e32 v16, 1, v16
	v_or_b32_e32 v16, v17, v16
	v_cvt_f32_u32_e32 v16, v16
	v_sub_u32_e32 v17, 32, v18
	v_ldexp_f32 v16, v16, v17
	v_fmamk_f32 v16, v16, 0x2e800000, v226
	v_cmp_gt_f32_e32 vcc, s31, v16
	v_mul_f32_e32 v17, 0x4f800000, v16
	s_nop 0
	v_cndmask_b32_e32 v16, v16, v17, vcc
	v_sqrt_f32_e32 v17, v16
	s_nop 0
	v_add_u32_e32 v18, -1, v17
	v_fma_f32 v19, -v18, v17, v16
	v_cmp_ge_f32_e64 s[42:43], 0, v19
	v_add_u32_e32 v19, 1, v17
	s_nop 0
	v_cndmask_b32_e64 v18, v17, v18, s[42:43]
	v_fma_f32 v17, -v19, v17, v16
	v_cmp_lt_f32_e64 s[42:43], 0, v17
	s_nop 1
	v_cndmask_b32_e64 v17, v18, v19, s[42:43]
	v_mul_f32_e32 v18, 0x37800000, v17
	v_cndmask_b32_e32 v17, v17, v18, vcc
	v_cmp_class_f32_e32 vcc, v16, v227
	s_nop 1
	v_cndmask_b32_e32 v16, v17, v16, vcc
	v_div_scale_f32 v17, s[0:1], v16, v16, 1.0
	v_rcp_f32_e32 v18, v17
	s_nop 0
	v_fma_f32 v19, -v17, v18, 1.0
	v_fmac_f32_e32 v18, v19, v18
	v_div_scale_f32 v19, vcc, 1.0, v16, 1.0
	v_mul_f32_e32 v20, v19, v18
	v_fma_f32 v21, -v17, v20, v19
	v_fmac_f32_e32 v20, v21, v18
	v_fma_f32 v17, -v17, v20, v19
	v_div_fmas_f32 v17, v17, v18, v20
	v_div_fixup_f32 v16, v17, v16, 1.0
	v_pk_mul_f32 v[12:13], v[12:13], v[16:17] op_sel_hi:[1,0]
	s_andn2_b64 vcc, exec, s[40:41]
	v_mul_f32_e32 v17, 0xbfb8aa3b, v12
	v_exp_f32_e32 v17, v17
	s_nop 0
	v_add_f32_e32 v17, 1.0, v17
	v_rcp_f32_e32 v18, v17
	v_mul_f32_e32 v17, 0xbfb8aa3b, v13
	v_exp_f32_e32 v17, v17
	s_nop 0
	v_add_f32_e32 v17, 1.0, v17
	v_rcp_f32_e32 v19, v17
	v_pk_mul_f32 v[8:9], v[8:9], v[16:17] op_sel_hi:[1,0]
	v_pk_mul_f32 v[10:11], v[10:11], v[16:17] op_sel_hi:[1,0]
	v_pk_mul_f32 v[4:5], v[4:5], v[16:17] op_sel_hi:[1,0]
	v_pk_mul_f32 v[12:13], v[12:13], v[18:19]
	v_pk_mul_f32 v[0:1], v[0:1], v[16:17] op_sel_hi:[1,0]
	v_pk_mul_f32 v[8:9], v[8:9], v[12:13]
	v_pk_mul_f32 v[12:13], v[14:15], v[16:17] op_sel_hi:[1,0]
	v_cvt_pk_bf16_f32 v8, v8, v9
	v_mul_f32_e32 v14, 0xbfb8aa3b, v12
	v_mul_f32_e32 v15, 0xbfb8aa3b, v13
	v_exp_f32_e32 v14, v14
	v_exp_f32_e32 v15, v15
	v_pk_mul_f32 v[2:3], v[2:3], v[16:17] op_sel_hi:[1,0]
	v_add_f32_e32 v14, 1.0, v14
	v_add_f32_e32 v15, 1.0, v15
	v_rcp_f32_e32 v14, v14
	v_rcp_f32_e32 v15, v15
	s_nop 0
	v_pk_mul_f32 v[12:13], v[12:13], v[14:15]
	s_nop 0
	v_pk_mul_f32 v[10:11], v[10:11], v[12:13]
	s_nop 0
	v_cvt_pk_bf16_f32 v9, v10, v11
	v_mul_f32_e32 v10, 0xbfb8aa3b, v4
	v_mul_f32_e32 v11, 0xbfb8aa3b, v5
	v_exp_f32_e32 v10, v10
	v_exp_f32_e32 v11, v11
	v_add_f32_e32 v10, 1.0, v10
	v_add_f32_e32 v11, 1.0, v11
	v_rcp_f32_e32 v10, v10
	v_rcp_f32_e32 v11, v11
	s_nop 0
	v_pk_mul_f32 v[4:5], v[4:5], v[10:11]
	s_nop 0
	v_pk_mul_f32 v[0:1], v[0:1], v[4:5]
	v_pk_mul_f32 v[4:5], v[6:7], v[16:17] op_sel_hi:[1,0]
	v_cvt_pk_bf16_f32 v10, v0, v1
	v_mul_f32_e32 v6, 0xbfb8aa3b, v4
	v_mul_f32_e32 v7, 0xbfb8aa3b, v5
	v_exp_f32_e32 v6, v6
	v_exp_f32_e32 v7, v7
	v_mad_i64_i32 v[0:1], s[0:1], v153, s82, v[112:113]
	v_add_f32_e32 v6, 1.0, v6
	v_add_f32_e32 v7, 1.0, v7
	v_rcp_f32_e32 v6, v6
	v_rcp_f32_e32 v7, v7
	v_lshl_add_u64 v[0:1], v[0:1], 0, v[114:115]
	s_mov_b64 s[0:1], -1
	v_pk_mul_f32 v[4:5], v[4:5], v[6:7]
	s_nop 0
	v_pk_mul_f32 v[2:3], v[2:3], v[4:5]
	s_nop 0
	v_cvt_pk_bf16_f32 v11, v2, v3
	global_store_dwordx4 v[0:1], v[8:11], off sc1 nt
	s_cbranch_vccnz .LBB0_77
	s_andn2_b64 vcc, exec, s[14:15]
	s_cbranch_vccnz .LBB0_76
	s_barrier
	s_branch .LBB0_76

; __device__ __forceinline__ unsigned cvtpk(float lo, float hi) { f32x2_t v = {lo, hi}; bf16x2_t b = __builtin_convertvector(v, bf16x2_t); return __builtin_bit_cast(unsigned, b); }
; __device__ __forceinline__ float ss_rs(u64 v) { return 1.f / sqrtf((float)v * (SSFI / 1024.f) + 1e-6f); }
;     __device__ __forceinline__ void operator()(const Acc& acc, const Unit& u, int wr, int wc, int fr, int fq) const {
;         const int row0 = u.pm * BM + wr * 64 + fr, col0 = u.pn * 128 + wc * 32 + 8 * fq;
;         u64 sv[2][4];
; #pragma unroll
;         for (int ai = 0; ai < 2; ++ai)
; #pragma unroll
;             for (int m = 0; m < 4; ++m) sv[ai][m] = SS[row0 + ai * HALF + m * 16];
; #pragma unroll
;         for (int ai = 0; ai < 2; ++ai)
; #pragma unroll
;             for (int m = 0; m < 4; ++m) {
;                 const int row = row0 + ai * HALF + m * 16; const float rs = ss_rs(sv[ai][m]);
;                 unsigned w[4];
; #pragma unroll
;                 for (int n = 0; n < 2; ++n) {
;                     const f32x4 gv = acc[ai][0][m][n] * rs, uv = acc[ai][1][m][n] * rs; float h[4];
; #pragma unroll
;                     for (int e = 0; e < 4; ++e) { const float gg = gv[e]; h[e] = gg * __builtin_amdgcn_rcpf(1.f + __builtin_amdgcn_exp2f(-1.4426950408889634f * gg)) * uv[e]; }
;                     w[2 * n] = cvtpk(h[0], h[1]); w[2 * n + 1] = cvtpk(h[2], h[3]);
;                 }
;                 *(u32x4*)(O + (size_t)row * DFF + col0) = (u32x4){w[0], w[1], w[2], w[3]};
.LBB0_1144:
	v_lshl_add_u32 v152, s0, 8, v156
	v_ashrrev_i32_e32 v153, 31, v152
	v_lshl_add_u64 v[138:139], v[152:153], 3, s[36:37]
	global_load_dwordx2 v[168:169], v[138:139], off
	global_load_dwordx2 v[150:151], v[138:139], off offset:128
	global_load_dwordx2 v[148:149], v[138:139], off offset:256
	global_load_dwordx2 v[146:147], v[138:139], off offset:384
	v_lshl_or_b32 v154, s1, 7, v158
	v_ashrrev_i32_e32 v155, 31, v154
	global_load_dwordx2 v[144:145], v[138:139], off offset:1024
	global_load_dwordx2 v[142:143], v[138:139], off offset:1152
	global_load_dwordx2 v[140:141], v[138:139], off offset:1280
	v_or_b32_e32 v167, 16, v152
	global_load_dwordx2 v[138:139], v[138:139], off offset:1408
	v_or_b32_e32 v166, 32, v152
	v_or_b32_e32 v165, 48, v152
	v_add_u32_e32 v164, 0x80, v152
	v_add_u32_e32 v163, 0x90, v152
	v_add_u32_e32 v162, 0xa0, v152
	v_add_u32_e32 v153, 0xb0, v152
	s_waitcnt vmcnt(0)
	v_ffbh_u32_e32 v170, v169
	v_min_u32_e32 v170, 32, v170
	v_lshlrev_b64 v[168:169], v170, v[168:169]
	v_min_u32_e32 v168, 1, v168
	v_or_b32_e32 v168, v169, v168
	v_cvt_f32_u32_e32 v168, v168
	v_sub_u32_e32 v169, 32, v170
	v_ldexp_f32 v168, v168, v169
	v_fmamk_f32 v168, v168, 0x2e800000, v226
	v_cmp_gt_f32_e32 vcc, s31, v168
	v_mul_f32_e32 v169, 0x4f800000, v168
	s_nop 0
	v_cndmask_b32_e32 v168, v168, v169, vcc
	v_sqrt_f32_e32 v169, v168
	s_nop 0
	v_add_u32_e32 v170, -1, v169
	v_fma_f32 v171, -v170, v169, v168
	v_cmp_ge_f32_e64 s[44:45], 0, v171
	v_add_u32_e32 v171, 1, v169
	s_nop 0
	v_cndmask_b32_e64 v170, v169, v170, s[44:45]
	v_fma_f32 v169, -v171, v169, v168
	v_cmp_lt_f32_e64 s[44:45], 0, v169
	s_nop 1
	v_cndmask_b32_e64 v169, v170, v171, s[44:45]
	v_mul_f32_e32 v170, 0x37800000, v169
	v_cndmask_b32_e32 v169, v169, v170, vcc
	v_cmp_class_f32_e32 vcc, v168, v227
	s_nop 1
	v_cndmask_b32_e32 v168, v169, v168, vcc
	v_div_scale_f32 v169, s[0:1], v168, v168, 1.0
	v_rcp_f32_e32 v170, v169
	s_nop 0
	v_fma_f32 v171, -v169, v170, 1.0
	v_fmac_f32_e32 v170, v171, v170
	v_div_scale_f32 v171, vcc, 1.0, v168, 1.0
	v_mul_f32_e32 v172, v171, v170
	v_fma_f32 v173, -v169, v172, v171
	v_fmac_f32_e32 v172, v173, v170
	v_fma_f32 v169, -v169, v172, v171
	v_div_fmas_f32 v169, v169, v170, v172
	v_div_fixup_f32 v168, v169, v168, 1.0
	v_pk_mul_f32 v[124:125], v[124:125], v[168:169] op_sel_hi:[1,0]
	s_nop 0
	v_mul_f32_e32 v169, 0xbfb8aa3b, v124
	v_exp_f32_e32 v169, v169
	s_nop 0
	v_add_f32_e32 v169, 1.0, v169
	v_rcp_f32_e32 v170, v169
	v_mul_f32_e32 v169, 0xbfb8aa3b, v125
	v_exp_f32_e32 v169, v169
	s_nop 0
	v_add_f32_e32 v169, 1.0, v169
	v_rcp_f32_e32 v171, v169
	v_pk_mul_f32 v[116:117], v[116:117], v[168:169] op_sel_hi:[1,0]
	v_pk_mul_f32 v[118:119], v[118:119], v[168:169] op_sel_hi:[1,0]
	v_pk_mul_f32 v[112:113], v[112:113], v[168:169] op_sel_hi:[1,0]
	v_pk_mul_f32 v[124:125], v[124:125], v[170:171]
	v_pk_mul_f32 v[114:115], v[114:115], v[168:169] op_sel_hi:[1,0]
	v_pk_mul_f32 v[116:117], v[116:117], v[124:125]
	v_pk_mul_f32 v[124:125], v[126:127], v[168:169] op_sel_hi:[1,0]
	v_cvt_pk_bf16_f32 v116, v116, v117
	v_mul_f32_e32 v126, 0xbfb8aa3b, v124
	v_mul_f32_e32 v127, 0xbfb8aa3b, v125
	v_exp_f32_e32 v126, v126
	v_exp_f32_e32 v127, v127
	v_add_f32_e32 v126, 1.0, v126
	v_add_f32_e32 v127, 1.0, v127
	v_rcp_f32_e32 v126, v126
	v_rcp_f32_e32 v127, v127
	s_nop 0
	v_pk_mul_f32 v[124:125], v[124:125], v[126:127]
	s_nop 0
	v_pk_mul_f32 v[118:119], v[118:119], v[124:125]
	s_nop 0
	v_cvt_pk_bf16_f32 v117, v118, v119
	v_pk_mul_f32 v[118:119], v[120:121], v[168:169] op_sel_hi:[1,0]
	s_nop 0
	v_mul_f32_e32 v120, 0xbfb8aa3b, v118
	v_mul_f32_e32 v121, 0xbfb8aa3b, v119
	v_exp_f32_e32 v120, v120
	v_exp_f32_e32 v121, v121
	v_add_f32_e32 v120, 1.0, v120
	v_add_f32_e32 v121, 1.0, v121
	v_rcp_f32_e32 v120, v120
	v_rcp_f32_e32 v121, v121
	s_nop 0
	v_pk_mul_f32 v[118:119], v[118:119], v[120:121]
	s_nop 0
	v_pk_mul_f32 v[112:113], v[112:113], v[118:119]
	v_pk_mul_f32 v[118:119], v[122:123], v[168:169] op_sel_hi:[1,0]
	s_nop 0
	v_mul_f32_e32 v120, 0xbfb8aa3b, v118
	v_mul_f32_e32 v121, 0xbfb8aa3b, v119
	v_exp_f32_e32 v120, v120
	v_exp_f32_e32 v121, v121
	v_add_f32_e32 v120, 1.0, v120
	v_add_f32_e32 v121, 1.0, v121
	v_rcp_f32_e32 v120, v120
	v_rcp_f32_e32 v121, v121
	s_nop 0
	v_pk_mul_f32 v[118:119], v[118:119], v[120:121]
	s_nop 0
	v_pk_mul_f32 v[114:115], v[114:115], v[118:119]
	v_cvt_pk_bf16_f32 v118, v112, v113
	v_mov_b64_e32 v[112:113], s[34:35]
	v_cvt_pk_bf16_f32 v119, v114, v115
	v_mad_i64_i32 v[120:121], s[0:1], v152, s82, v[112:113]
	v_lshlrev_b64 v[114:115], 1, v[154:155]
	v_lshl_add_u64 v[120:121], v[120:121], 0, v[114:115]
	global_store_dwordx4 v[120:121], v[116:119], off sc1 nt
	s_nop 1
	v_ffbh_u32_e32 v116, v151
	v_min_u32_e32 v118, 32, v116
	v_lshlrev_b64 v[116:117], v118, v[150:151]
	v_min_u32_e32 v116, 1, v116
	v_or_b32_e32 v116, v117, v116
	v_cvt_f32_u32_e32 v116, v116
	v_sub_u32_e32 v117, 32, v118
	v_ldexp_f32 v116, v116, v117
	v_fmamk_f32 v116, v116, 0x2e800000, v226
	v_cmp_gt_f32_e32 vcc, s31, v116
	v_mul_f32_e32 v117, 0x4f800000, v116
	s_nop 0
	v_cndmask_b32_e32 v116, v116, v117, vcc
	v_sqrt_f32_e32 v117, v116
	s_nop 0
	v_add_u32_e32 v118, -1, v117
	v_fma_f32 v119, -v118, v117, v116
	v_cmp_ge_f32_e64 s[44:45], 0, v119
	v_add_u32_e32 v119, 1, v117
	s_nop 0
	v_cndmask_b32_e64 v118, v117, v118, s[44:45]
	v_fma_f32 v117, -v119, v117, v116
	v_cmp_lt_f32_e64 s[44:45], 0, v117
	s_nop 1
	v_cndmask_b32_e64 v117, v118, v119, s[44:45]
	v_mul_f32_e32 v118, 0x37800000, v117
	v_cndmask_b32_e32 v117, v117, v118, vcc
	v_cmp_class_f32_e32 vcc, v116, v227
	s_nop 1
	v_cndmask_b32_e32 v116, v117, v116, vcc
	v_div_scale_f32 v117, s[0:1], v116, v116, 1.0
	v_rcp_f32_e32 v118, v117
	s_nop 0
; __device__ __forceinline__ unsigned cvtpk(float lo, float hi) { f32x2_t v = {lo, hi}; bf16x2_t b = __builtin_convertvector(v, bf16x2_t); return __builtin_bit_cast(unsigned, b); }
; __device__ __forceinline__ float ss_rs(u64 v) { return 1.f / sqrtf((float)v * (SSFI / 1024.f) + 1e-6f); }
;     __device__ __forceinline__ void operator()(const Acc& acc, const Unit& u, int wr, int wc, int fr, int fq) const {
;     ...
;                 const int row = row0 + ai * HALF + m * 16; const float rs = ss_rs(sv[ai][m]);
;                 unsigned w[4];
; #pragma unroll
;                 for (int n = 0; n < 2; ++n) {
;                     const f32x4 gv = acc[ai][0][m][n] * rs, uv = acc[ai][1][m][n] * rs; float h[4];
; #pragma unroll
;                     for (int e = 0; e < 4; ++e) { const float gg = gv[e]; h[e] = gg * __builtin_amdgcn_rcpf(1.f + __builtin_amdgcn_exp2f(-1.4426950408889634f * gg)) * uv[e]; }
;                     w[2 * n] = cvtpk(h[0], h[1]); w[2 * n + 1] = cvtpk(h[2], h[3]);
;                 }
;                 *(u32x4*)(O + (size_t)row * DFF + col0) = (u32x4){w[0], w[1], w[2], w[3]};
	v_fma_f32 v119, -v117, v118, 1.0
	v_fmac_f32_e32 v118, v119, v118
	v_div_scale_f32 v119, vcc, 1.0, v116, 1.0
	v_mul_f32_e32 v120, v119, v118
	v_fma_f32 v121, -v117, v120, v119
	v_fmac_f32_e32 v120, v121, v118
	v_fma_f32 v117, -v117, v120, v119
	v_div_fmas_f32 v117, v117, v118, v120
	v_div_fixup_f32 v116, v117, v116, 1.0
	v_pk_mul_f32 v[108:109], v[108:109], v[116:117] op_sel_hi:[1,0]
	s_nop 0
	v_mul_f32_e32 v117, 0xbfb8aa3b, v108
	v_exp_f32_e32 v117, v117
	s_nop 0
	v_add_f32_e32 v117, 1.0, v117
	v_rcp_f32_e32 v118, v117
	v_mul_f32_e32 v117, 0xbfb8aa3b, v109
	v_exp_f32_e32 v117, v117
	s_nop 0
	v_add_f32_e32 v117, 1.0, v117
	v_rcp_f32_e32 v119, v117
	v_pk_mul_f32 v[104:105], v[104:105], v[116:117] op_sel_hi:[1,0]
	v_pk_mul_f32 v[106:107], v[106:107], v[116:117] op_sel_hi:[1,0]
	v_pk_mul_f32 v[100:101], v[100:101], v[116:117] op_sel_hi:[1,0]
	v_pk_mul_f32 v[108:109], v[108:109], v[118:119]
	v_pk_mul_f32 v[96:97], v[96:97], v[116:117] op_sel_hi:[1,0]
	v_pk_mul_f32 v[104:105], v[104:105], v[108:109]
	v_pk_mul_f32 v[108:109], v[110:111], v[116:117] op_sel_hi:[1,0]
	v_cvt_pk_bf16_f32 v104, v104, v105
	v_mul_f32_e32 v110, 0xbfb8aa3b, v108
	v_mul_f32_e32 v111, 0xbfb8aa3b, v109
	v_exp_f32_e32 v110, v110
	v_exp_f32_e32 v111, v111
	v_pk_mul_f32 v[98:99], v[98:99], v[116:117] op_sel_hi:[1,0]
	v_add_f32_e32 v110, 1.0, v110
	v_add_f32_e32 v111, 1.0, v111
	v_rcp_f32_e32 v110, v110
	v_rcp_f32_e32 v111, v111
	s_nop 0
	v_pk_mul_f32 v[108:109], v[108:109], v[110:111]
	s_nop 0
	v_pk_mul_f32 v[106:107], v[106:107], v[108:109]
	s_nop 0
	v_cvt_pk_bf16_f32 v105, v106, v107
	v_mul_f32_e32 v106, 0xbfb8aa3b, v100
	v_mul_f32_e32 v107, 0xbfb8aa3b, v101
	v_exp_f32_e32 v106, v106
	v_exp_f32_e32 v107, v107
	v_add_f32_e32 v106, 1.0, v106
	v_add_f32_e32 v107, 1.0, v107
	v_rcp_f32_e32 v106, v106
	v_rcp_f32_e32 v107, v107
	s_nop 0
	v_pk_mul_f32 v[100:101], v[100:101], v[106:107]
	s_nop 0
	v_pk_mul_f32 v[96:97], v[96:97], v[100:101]
	v_pk_mul_f32 v[100:101], v[102:103], v[116:117] op_sel_hi:[1,0]
	v_cvt_pk_bf16_f32 v106, v96, v97
	v_mul_f32_e32 v102, 0xbfb8aa3b, v100
	v_mul_f32_e32 v103, 0xbfb8aa3b, v101
	v_exp_f32_e32 v102, v102
	v_exp_f32_e32 v103, v103
	v_mad_i64_i32 v[96:97], s[0:1], v167, s82, v[112:113]
	v_add_f32_e32 v102, 1.0, v102
	v_add_f32_e32 v103, 1.0, v103
	v_rcp_f32_e32 v102, v102
	v_rcp_f32_e32 v103, v103
	v_lshl_add_u64 v[96:97], v[96:97], 0, v[114:115]
	v_pk_mul_f32 v[100:101], v[100:101], v[102:103]
	s_nop 0
	v_pk_mul_f32 v[98:99], v[98:99], v[100:101]
	s_nop 0
	v_cvt_pk_bf16_f32 v107, v98, v99
	global_store_dwordx4 v[96:97], v[104:107], off sc1 nt
	v_ffbh_u32_e32 v96, v149
	v_min_u32_e32 v98, 32, v96
	v_lshlrev_b64 v[96:97], v98, v[148:149]
	v_min_u32_e32 v96, 1, v96
	v_or_b32_e32 v96, v97, v96
	v_cvt_f32_u32_e32 v96, v96
	v_sub_u32_e32 v97, 32, v98
	v_ldexp_f32 v96, v96, v97
	v_fmamk_f32 v96, v96, 0x2e800000, v226
	v_cmp_gt_f32_e32 vcc, s31, v96
	v_mul_f32_e32 v97, 0x4f800000, v96
	s_nop 0
	v_cndmask_b32_e32 v96, v96, v97, vcc
	v_sqrt_f32_e32 v97, v96
	s_nop 0
	v_add_u32_e32 v98, -1, v97
	v_fma_f32 v99, -v98, v97, v96
	v_cmp_ge_f32_e64 s[44:45], 0, v99
	v_add_u32_e32 v99, 1, v97
	s_nop 0
	v_cndmask_b32_e64 v98, v97, v98, s[44:45]
	v_fma_f32 v97, -v99, v97, v96
	v_cmp_lt_f32_e64 s[44:45], 0, v97
	s_nop 1
	v_cndmask_b32_e64 v97, v98, v99, s[44:45]
	v_mul_f32_e32 v98, 0x37800000, v97
	v_cndmask_b32_e32 v97, v97, v98, vcc
	v_cmp_class_f32_e32 vcc, v96, v227
	s_nop 1
	v_cndmask_b32_e32 v96, v97, v96, vcc
	v_div_scale_f32 v97, s[0:1], v96, v96, 1.0
	v_rcp_f32_e32 v98, v97
	s_nop 0
	v_fma_f32 v99, -v97, v98, 1.0
	v_fmac_f32_e32 v98, v99, v98
	v_div_scale_f32 v99, vcc, 1.0, v96, 1.0
	v_mul_f32_e32 v100, v99, v98
	v_fma_f32 v101, -v97, v100, v99
	v_fmac_f32_e32 v100, v101, v98
	v_fma_f32 v97, -v97, v100, v99
	v_div_fmas_f32 v97, v97, v98, v100
	v_div_fixup_f32 v96, v97, v96, 1.0
	v_pk_mul_f32 v[92:93], v[92:93], v[96:97] op_sel_hi:[1,0]
	s_nop 0
	v_mul_f32_e32 v97, 0xbfb8aa3b, v92
	v_exp_f32_e32 v97, v97
	s_nop 0
	v_add_f32_e32 v97, 1.0, v97
	v_rcp_f32_e32 v98, v97
	v_mul_f32_e32 v97, 0xbfb8aa3b, v93
	v_exp_f32_e32 v97, v97
	s_nop 0
	v_add_f32_e32 v97, 1.0, v97
	v_rcp_f32_e32 v99, v97
	v_pk_mul_f32 v[88:89], v[88:89], v[96:97] op_sel_hi:[1,0]
	v_pk_mul_f32 v[90:91], v[90:91], v[96:97] op_sel_hi:[1,0]
	v_pk_mul_f32 v[84:85], v[84:85], v[96:97] op_sel_hi:[1,0]
	v_pk_mul_f32 v[92:93], v[92:93], v[98:99]
	v_pk_mul_f32 v[80:81], v[80:81], v[96:97] op_sel_hi:[1,0]
	v_pk_mul_f32 v[88:89], v[88:89], v[92:93]
	v_pk_mul_f32 v[92:93], v[94:95], v[96:97] op_sel_hi:[1,0]
	v_cvt_pk_bf16_f32 v88, v88, v89
	v_mul_f32_e32 v94, 0xbfb8aa3b, v92
	v_mul_f32_e32 v95, 0xbfb8aa3b, v93
	v_exp_f32_e32 v94, v94
	v_exp_f32_e32 v95, v95
	v_pk_mul_f32 v[82:83], v[82:83], v[96:97] op_sel_hi:[1,0]
	v_add_f32_e32 v94, 1.0, v94
	v_add_f32_e32 v95, 1.0, v95
	v_rcp_f32_e32 v94, v94
	v_rcp_f32_e32 v95, v95
	s_nop 0
	v_pk_mul_f32 v[92:93], v[92:93], v[94:95]
	s_nop 0
	v_pk_mul_f32 v[90:91], v[90:91], v[92:93]
	s_nop 0
	v_cvt_pk_bf16_f32 v89, v90, v91
	v_mul_f32_e32 v90, 0xbfb8aa3b, v84
	v_mul_f32_e32 v91, 0xbfb8aa3b, v85
	v_exp_f32_e32 v90, v90
	v_exp_f32_e32 v91, v91
	v_add_f32_e32 v90, 1.0, v90
	v_add_f32_e32 v91, 1.0, v91
	v_rcp_f32_e32 v90, v90
	v_rcp_f32_e32 v91, v91
	s_nop 0
	v_pk_mul_f32 v[84:85], v[84:85], v[90:91]
	s_nop 0
	v_pk_mul_f32 v[80:81], v[80:81], v[84:85]
	v_pk_mul_f32 v[84:85], v[86:87], v[96:97] op_sel_hi:[1,0]
	v_cvt_pk_bf16_f32 v90, v80, v81
	v_mul_f32_e32 v86, 0xbfb8aa3b, v84
	v_mul_f32_e32 v87, 0xbfb8aa3b, v85
	v_exp_f32_e32 v86, v86
	v_exp_f32_e32 v87, v87
	v_mad_i64_i32 v[80:81], s[0:1], v166, s82, v[112:113]
	v_add_f32_e32 v86, 1.0, v86
	v_add_f32_e32 v87, 1.0, v87
; __device__ __forceinline__ unsigned cvtpk(float lo, float hi) { f32x2_t v = {lo, hi}; bf16x2_t b = __builtin_convertvector(v, bf16x2_t); return __builtin_bit_cast(unsigned, b); }
; __device__ __forceinline__ float ss_rs(u64 v) { return 1.f / sqrtf((float)v * (SSFI / 1024.f) + 1e-6f); }
;     __device__ __forceinline__ void operator()(const Acc& acc, const Unit& u, int wr, int wc, int fr, int fq) const {
;     ...
;                 const int row = row0 + ai * HALF + m * 16; const float rs = ss_rs(sv[ai][m]);
;                 unsigned w[4];
; #pragma unroll
;                 for (int n = 0; n < 2; ++n) {
;                     const f32x4 gv = acc[ai][0][m][n] * rs, uv = acc[ai][1][m][n] * rs; float h[4];
; #pragma unroll
;                     for (int e = 0; e < 4; ++e) { const float gg = gv[e]; h[e] = gg * __builtin_amdgcn_rcpf(1.f + __builtin_amdgcn_exp2f(-1.4426950408889634f * gg)) * uv[e]; }
;                     w[2 * n] = cvtpk(h[0], h[1]); w[2 * n + 1] = cvtpk(h[2], h[3]);
;                 }
;                 *(u32x4*)(O + (size_t)row * DFF + col0) = (u32x4){w[0], w[1], w[2], w[3]};
	v_rcp_f32_e32 v86, v86
	v_rcp_f32_e32 v87, v87
	v_lshl_add_u64 v[80:81], v[80:81], 0, v[114:115]
	v_pk_mul_f32 v[84:85], v[84:85], v[86:87]
	s_nop 0
	v_pk_mul_f32 v[82:83], v[82:83], v[84:85]
	s_nop 0
	v_cvt_pk_bf16_f32 v91, v82, v83
	global_store_dwordx4 v[80:81], v[88:91], off sc1 nt
	v_ffbh_u32_e32 v80, v147
	v_min_u32_e32 v82, 32, v80
	v_lshlrev_b64 v[80:81], v82, v[146:147]
	v_min_u32_e32 v80, 1, v80
	v_or_b32_e32 v80, v81, v80
	v_cvt_f32_u32_e32 v80, v80
	v_sub_u32_e32 v81, 32, v82
	v_ldexp_f32 v80, v80, v81
	v_fmamk_f32 v80, v80, 0x2e800000, v226
	v_cmp_gt_f32_e32 vcc, s31, v80
	v_mul_f32_e32 v81, 0x4f800000, v80
	s_nop 0
	v_cndmask_b32_e32 v80, v80, v81, vcc
	v_sqrt_f32_e32 v81, v80
	s_nop 0
	v_add_u32_e32 v82, -1, v81
	v_fma_f32 v83, -v82, v81, v80
	v_cmp_ge_f32_e64 s[44:45], 0, v83
	v_add_u32_e32 v83, 1, v81
	s_nop 0
	v_cndmask_b32_e64 v82, v81, v82, s[44:45]
	v_fma_f32 v81, -v83, v81, v80
	v_cmp_lt_f32_e64 s[44:45], 0, v81
	s_nop 1
	v_cndmask_b32_e64 v81, v82, v83, s[44:45]
	v_mul_f32_e32 v82, 0x37800000, v81
	v_cndmask_b32_e32 v81, v81, v82, vcc
	v_cmp_class_f32_e32 vcc, v80, v227
	s_nop 1
	v_cndmask_b32_e32 v80, v81, v80, vcc
	v_div_scale_f32 v81, s[0:1], v80, v80, 1.0
	v_rcp_f32_e32 v82, v81
	s_nop 0
	v_fma_f32 v83, -v81, v82, 1.0
	v_fmac_f32_e32 v82, v83, v82
	v_div_scale_f32 v83, vcc, 1.0, v80, 1.0
	v_mul_f32_e32 v84, v83, v82
	v_fma_f32 v85, -v81, v84, v83
	v_fmac_f32_e32 v84, v85, v82
	v_fma_f32 v81, -v81, v84, v83
	v_div_fmas_f32 v81, v81, v82, v84
	v_div_fixup_f32 v80, v81, v80, 1.0
	v_pk_mul_f32 v[76:77], v[76:77], v[80:81] op_sel_hi:[1,0]
	s_nop 0
	v_mul_f32_e32 v81, 0xbfb8aa3b, v76
	v_exp_f32_e32 v81, v81
	s_nop 0
	v_add_f32_e32 v81, 1.0, v81
	v_rcp_f32_e32 v82, v81
	v_mul_f32_e32 v81, 0xbfb8aa3b, v77
	v_exp_f32_e32 v81, v81
	s_nop 0
	v_add_f32_e32 v81, 1.0, v81
	v_rcp_f32_e32 v83, v81
	v_pk_mul_f32 v[72:73], v[72:73], v[80:81] op_sel_hi:[1,0]
	v_pk_mul_f32 v[74:75], v[74:75], v[80:81] op_sel_hi:[1,0]
	v_pk_mul_f32 v[68:69], v[68:69], v[80:81] op_sel_hi:[1,0]
	v_pk_mul_f32 v[76:77], v[76:77], v[82:83]
	v_pk_mul_f32 v[64:65], v[64:65], v[80:81] op_sel_hi:[1,0]
	v_pk_mul_f32 v[72:73], v[72:73], v[76:77]
	v_pk_mul_f32 v[76:77], v[78:79], v[80:81] op_sel_hi:[1,0]
	v_cvt_pk_bf16_f32 v72, v72, v73
	v_mul_f32_e32 v78, 0xbfb8aa3b, v76
	v_mul_f32_e32 v79, 0xbfb8aa3b, v77
	v_exp_f32_e32 v78, v78
	v_exp_f32_e32 v79, v79
	v_pk_mul_f32 v[66:67], v[66:67], v[80:81] op_sel_hi:[1,0]
	v_add_f32_e32 v78, 1.0, v78
	v_add_f32_e32 v79, 1.0, v79
	v_rcp_f32_e32 v78, v78
	v_rcp_f32_e32 v79, v79
	s_nop 0
	v_pk_mul_f32 v[76:77], v[76:77], v[78:79]
	s_nop 0
	v_pk_mul_f32 v[74:75], v[74:75], v[76:77]
	s_nop 0
	v_cvt_pk_bf16_f32 v73, v74, v75
	v_mul_f32_e32 v74, 0xbfb8aa3b, v68
	v_mul_f32_e32 v75, 0xbfb8aa3b, v69
	v_exp_f32_e32 v74, v74
	v_exp_f32_e32 v75, v75
	v_add_f32_e32 v74, 1.0, v74
	v_add_f32_e32 v75, 1.0, v75
	v_rcp_f32_e32 v74, v74
	v_rcp_f32_e32 v75, v75
	s_nop 0
	v_pk_mul_f32 v[68:69], v[68:69], v[74:75]
	s_nop 0
	v_pk_mul_f32 v[64:65], v[64:65], v[68:69]
	v_pk_mul_f32 v[68:69], v[70:71], v[80:81] op_sel_hi:[1,0]
	v_cvt_pk_bf16_f32 v74, v64, v65
	v_mul_f32_e32 v70, 0xbfb8aa3b, v68
	v_mul_f32_e32 v71, 0xbfb8aa3b, v69
	v_exp_f32_e32 v70, v70
	v_exp_f32_e32 v71, v71
	v_mad_i64_i32 v[64:65], s[0:1], v165, s82, v[112:113]
	v_add_f32_e32 v70, 1.0, v70
	v_add_f32_e32 v71, 1.0, v71
	v_rcp_f32_e32 v70, v70
	v_rcp_f32_e32 v71, v71
	v_lshl_add_u64 v[64:65], v[64:65], 0, v[114:115]
	v_pk_mul_f32 v[68:69], v[68:69], v[70:71]
	s_nop 0
	v_pk_mul_f32 v[66:67], v[66:67], v[68:69]
	s_nop 0
	v_cvt_pk_bf16_f32 v75, v66, v67
	global_store_dwordx4 v[64:65], v[72:75], off sc1 nt
	v_ffbh_u32_e32 v64, v145
	v_min_u32_e32 v66, 32, v64
	v_lshlrev_b64 v[64:65], v66, v[144:145]
	v_min_u32_e32 v64, 1, v64
	v_or_b32_e32 v64, v65, v64
	v_cvt_f32_u32_e32 v64, v64
	v_sub_u32_e32 v65, 32, v66
	v_ldexp_f32 v64, v64, v65
	v_fmamk_f32 v64, v64, 0x2e800000, v226
	v_cmp_gt_f32_e32 vcc, s31, v64
	v_mul_f32_e32 v65, 0x4f800000, v64
	s_nop 0
	v_cndmask_b32_e32 v64, v64, v65, vcc
	v_sqrt_f32_e32 v65, v64
	s_nop 0
	v_add_u32_e32 v66, -1, v65
	v_fma_f32 v67, -v66, v65, v64
	v_cmp_ge_f32_e64 s[44:45], 0, v67
	v_add_u32_e32 v67, 1, v65
	s_nop 0
	v_cndmask_b32_e64 v66, v65, v66, s[44:45]
	v_fma_f32 v65, -v67, v65, v64
	v_cmp_lt_f32_e64 s[44:45], 0, v65
	s_nop 1
	v_cndmask_b32_e64 v65, v66, v67, s[44:45]
	v_mul_f32_e32 v66, 0x37800000, v65
	v_cndmask_b32_e32 v65, v65, v66, vcc
	v_cmp_class_f32_e32 vcc, v64, v227
	s_nop 1
	v_cndmask_b32_e32 v64, v65, v64, vcc
	v_div_scale_f32 v65, s[0:1], v64, v64, 1.0
	v_rcp_f32_e32 v66, v65
	s_nop 0
	v_fma_f32 v67, -v65, v66, 1.0
	v_fmac_f32_e32 v66, v67, v66
	v_div_scale_f32 v67, vcc, 1.0, v64, 1.0
	v_mul_f32_e32 v68, v67, v66
	v_fma_f32 v69, -v65, v68, v67
	v_fmac_f32_e32 v68, v69, v66
	v_fma_f32 v65, -v65, v68, v67
	v_div_fmas_f32 v65, v65, v66, v68
	v_div_fixup_f32 v64, v65, v64, 1.0
	v_pk_mul_f32 v[60:61], v[60:61], v[64:65] op_sel_hi:[1,0]
	s_nop 0
	v_mul_f32_e32 v65, 0xbfb8aa3b, v60
	v_exp_f32_e32 v65, v65
	s_nop 0
	v_add_f32_e32 v65, 1.0, v65
	v_rcp_f32_e32 v66, v65
	v_mul_f32_e32 v65, 0xbfb8aa3b, v61
	v_exp_f32_e32 v65, v65
	s_nop 0
	v_add_f32_e32 v65, 1.0, v65
	v_rcp_f32_e32 v67, v65
	v_pk_mul_f32 v[56:57], v[56:57], v[64:65] op_sel_hi:[1,0]
	v_pk_mul_f32 v[58:59], v[58:59], v[64:65] op_sel_hi:[1,0]
	v_pk_mul_f32 v[52:53], v[52:53], v[64:65] op_sel_hi:[1,0]
	v_pk_mul_f32 v[60:61], v[60:61], v[66:67]
	v_pk_mul_f32 v[48:49], v[48:49], v[64:65] op_sel_hi:[1,0]
	v_pk_mul_f32 v[56:57], v[56:57], v[60:61]
	v_pk_mul_f32 v[60:61], v[62:63], v[64:65] op_sel_hi:[1,0]
	v_cvt_pk_bf16_f32 v56, v56, v57
	v_mul_f32_e32 v62, 0xbfb8aa3b, v60
; __device__ __forceinline__ unsigned cvtpk(float lo, float hi) { f32x2_t v = {lo, hi}; bf16x2_t b = __builtin_convertvector(v, bf16x2_t); return __builtin_bit_cast(unsigned, b); }
; __device__ __forceinline__ float ss_rs(u64 v) { return 1.f / sqrtf((float)v * (SSFI / 1024.f) + 1e-6f); }
;     __device__ __forceinline__ void operator()(const Acc& acc, const Unit& u, int wr, int wc, int fr, int fq) const {
;     ...
;                 const int row = row0 + ai * HALF + m * 16; const float rs = ss_rs(sv[ai][m]);
;                 unsigned w[4];
; #pragma unroll
;                 for (int n = 0; n < 2; ++n) {
;                     const f32x4 gv = acc[ai][0][m][n] * rs, uv = acc[ai][1][m][n] * rs; float h[4];
; #pragma unroll
;                     for (int e = 0; e < 4; ++e) { const float gg = gv[e]; h[e] = gg * __builtin_amdgcn_rcpf(1.f + __builtin_amdgcn_exp2f(-1.4426950408889634f * gg)) * uv[e]; }
;                     w[2 * n] = cvtpk(h[0], h[1]); w[2 * n + 1] = cvtpk(h[2], h[3]);
;                 }
;                 *(u32x4*)(O + (size_t)row * DFF + col0) = (u32x4){w[0], w[1], w[2], w[3]};
	v_mul_f32_e32 v63, 0xbfb8aa3b, v61
	v_exp_f32_e32 v62, v62
	v_exp_f32_e32 v63, v63
	v_pk_mul_f32 v[50:51], v[50:51], v[64:65] op_sel_hi:[1,0]
	v_add_f32_e32 v62, 1.0, v62
	v_add_f32_e32 v63, 1.0, v63
	v_rcp_f32_e32 v62, v62
	v_rcp_f32_e32 v63, v63
	s_nop 0
	v_pk_mul_f32 v[60:61], v[60:61], v[62:63]
	s_nop 0
	v_pk_mul_f32 v[58:59], v[58:59], v[60:61]
	s_nop 0
	v_cvt_pk_bf16_f32 v57, v58, v59
	v_mul_f32_e32 v58, 0xbfb8aa3b, v52
	v_mul_f32_e32 v59, 0xbfb8aa3b, v53
	v_exp_f32_e32 v58, v58
	v_exp_f32_e32 v59, v59
	v_add_f32_e32 v58, 1.0, v58
	v_add_f32_e32 v59, 1.0, v59
	v_rcp_f32_e32 v58, v58
	v_rcp_f32_e32 v59, v59
	s_nop 0
	v_pk_mul_f32 v[52:53], v[52:53], v[58:59]
	s_nop 0
	v_pk_mul_f32 v[48:49], v[48:49], v[52:53]
	v_pk_mul_f32 v[52:53], v[54:55], v[64:65] op_sel_hi:[1,0]
	v_cvt_pk_bf16_f32 v58, v48, v49
	v_mul_f32_e32 v54, 0xbfb8aa3b, v52
	v_mul_f32_e32 v55, 0xbfb8aa3b, v53
	v_exp_f32_e32 v54, v54
	v_exp_f32_e32 v55, v55
	v_mad_i64_i32 v[48:49], s[0:1], v164, s82, v[112:113]
	v_add_f32_e32 v54, 1.0, v54
	v_add_f32_e32 v55, 1.0, v55
	v_rcp_f32_e32 v54, v54
	v_rcp_f32_e32 v55, v55
	v_lshl_add_u64 v[48:49], v[48:49], 0, v[114:115]
	v_pk_mul_f32 v[52:53], v[52:53], v[54:55]
	s_nop 0
	v_pk_mul_f32 v[50:51], v[50:51], v[52:53]
	s_nop 0
	v_cvt_pk_bf16_f32 v59, v50, v51
	global_store_dwordx4 v[48:49], v[56:59], off sc1 nt
	v_ffbh_u32_e32 v48, v143
	v_min_u32_e32 v50, 32, v48
	v_lshlrev_b64 v[48:49], v50, v[142:143]
	v_min_u32_e32 v48, 1, v48
	v_or_b32_e32 v48, v49, v48
	v_cvt_f32_u32_e32 v48, v48
	v_sub_u32_e32 v49, 32, v50
	v_ldexp_f32 v48, v48, v49
	v_fmamk_f32 v48, v48, 0x2e800000, v226
	v_cmp_gt_f32_e32 vcc, s31, v48
	v_mul_f32_e32 v49, 0x4f800000, v48
	s_nop 0
	v_cndmask_b32_e32 v48, v48, v49, vcc
	v_sqrt_f32_e32 v49, v48
	s_nop 0
	v_add_u32_e32 v50, -1, v49
	v_fma_f32 v51, -v50, v49, v48
	v_cmp_ge_f32_e64 s[44:45], 0, v51
	v_add_u32_e32 v51, 1, v49
	s_nop 0
	v_cndmask_b32_e64 v50, v49, v50, s[44:45]
	v_fma_f32 v49, -v51, v49, v48
	v_cmp_lt_f32_e64 s[44:45], 0, v49
	s_nop 1
	v_cndmask_b32_e64 v49, v50, v51, s[44:45]
	v_mul_f32_e32 v50, 0x37800000, v49
	v_cndmask_b32_e32 v49, v49, v50, vcc
	v_cmp_class_f32_e32 vcc, v48, v227
	s_nop 1
	v_cndmask_b32_e32 v48, v49, v48, vcc
	v_div_scale_f32 v49, s[0:1], v48, v48, 1.0
	v_rcp_f32_e32 v50, v49
	s_nop 0
	v_fma_f32 v51, -v49, v50, 1.0
	v_fmac_f32_e32 v50, v51, v50
	v_div_scale_f32 v51, vcc, 1.0, v48, 1.0
	v_mul_f32_e32 v52, v51, v50
	v_fma_f32 v53, -v49, v52, v51
	v_fmac_f32_e32 v52, v53, v50
	v_fma_f32 v49, -v49, v52, v51
	v_div_fmas_f32 v49, v49, v50, v52
	v_div_fixup_f32 v48, v49, v48, 1.0
	v_pk_mul_f32 v[44:45], v[44:45], v[48:49] op_sel_hi:[1,0]
	s_nop 0
	v_mul_f32_e32 v49, 0xbfb8aa3b, v44
	v_exp_f32_e32 v49, v49
	s_nop 0
	v_add_f32_e32 v49, 1.0, v49
	v_rcp_f32_e32 v50, v49
	v_mul_f32_e32 v49, 0xbfb8aa3b, v45
	v_exp_f32_e32 v49, v49
	s_nop 0
	v_add_f32_e32 v49, 1.0, v49
	v_rcp_f32_e32 v51, v49
	v_pk_mul_f32 v[40:41], v[40:41], v[48:49] op_sel_hi:[1,0]
	v_pk_mul_f32 v[42:43], v[42:43], v[48:49] op_sel_hi:[1,0]
	v_pk_mul_f32 v[36:37], v[36:37], v[48:49] op_sel_hi:[1,0]
	v_pk_mul_f32 v[44:45], v[44:45], v[50:51]
	v_pk_mul_f32 v[32:33], v[32:33], v[48:49] op_sel_hi:[1,0]
	v_pk_mul_f32 v[40:41], v[40:41], v[44:45]
	v_pk_mul_f32 v[44:45], v[46:47], v[48:49] op_sel_hi:[1,0]
	v_cvt_pk_bf16_f32 v40, v40, v41
	v_mul_f32_e32 v46, 0xbfb8aa3b, v44
	v_mul_f32_e32 v47, 0xbfb8aa3b, v45
	v_exp_f32_e32 v46, v46
	v_exp_f32_e32 v47, v47
	v_pk_mul_f32 v[34:35], v[34:35], v[48:49] op_sel_hi:[1,0]
	v_add_f32_e32 v46, 1.0, v46
	v_add_f32_e32 v47, 1.0, v47
	v_rcp_f32_e32 v46, v46
	v_rcp_f32_e32 v47, v47
	s_nop 0
	v_pk_mul_f32 v[44:45], v[44:45], v[46:47]
	s_nop 0
	v_pk_mul_f32 v[42:43], v[42:43], v[44:45]
	s_nop 0
	v_cvt_pk_bf16_f32 v41, v42, v43
	v_mul_f32_e32 v42, 0xbfb8aa3b, v36
	v_mul_f32_e32 v43, 0xbfb8aa3b, v37
	v_exp_f32_e32 v42, v42
	v_exp_f32_e32 v43, v43
	v_add_f32_e32 v42, 1.0, v42
	v_add_f32_e32 v43, 1.0, v43
	v_rcp_f32_e32 v42, v42
	v_rcp_f32_e32 v43, v43
	s_nop 0
	v_pk_mul_f32 v[36:37], v[36:37], v[42:43]
	s_nop 0
	v_pk_mul_f32 v[32:33], v[32:33], v[36:37]
	v_pk_mul_f32 v[36:37], v[38:39], v[48:49] op_sel_hi:[1,0]
	v_cvt_pk_bf16_f32 v42, v32, v33
	v_mul_f32_e32 v38, 0xbfb8aa3b, v36
	v_mul_f32_e32 v39, 0xbfb8aa3b, v37
	v_exp_f32_e32 v38, v38
	v_exp_f32_e32 v39, v39
	v_mad_i64_i32 v[32:33], s[0:1], v163, s82, v[112:113]
	v_add_f32_e32 v38, 1.0, v38
	v_add_f32_e32 v39, 1.0, v39
	v_rcp_f32_e32 v38, v38
	v_rcp_f32_e32 v39, v39
	v_lshl_add_u64 v[32:33], v[32:33], 0, v[114:115]
	v_pk_mul_f32 v[36:37], v[36:37], v[38:39]
	s_nop 0
	v_pk_mul_f32 v[34:35], v[34:35], v[36:37]
	s_nop 0
	v_cvt_pk_bf16_f32 v43, v34, v35
	global_store_dwordx4 v[32:33], v[40:43], off sc1 nt
	v_ffbh_u32_e32 v32, v141
	v_min_u32_e32 v34, 32, v32
	v_lshlrev_b64 v[32:33], v34, v[140:141]
	v_min_u32_e32 v32, 1, v32
	v_or_b32_e32 v32, v33, v32
	v_cvt_f32_u32_e32 v32, v32
	v_sub_u32_e32 v33, 32, v34
	v_ldexp_f32 v32, v32, v33
	v_fmamk_f32 v32, v32, 0x2e800000, v226
	v_cmp_gt_f32_e32 vcc, s31, v32
	v_mul_f32_e32 v33, 0x4f800000, v32
	s_nop 0
	v_cndmask_b32_e32 v32, v32, v33, vcc
	v_sqrt_f32_e32 v33, v32
	s_nop 0
	v_add_u32_e32 v34, -1, v33
	v_fma_f32 v35, -v34, v33, v32
	v_cmp_ge_f32_e64 s[44:45], 0, v35
	v_add_u32_e32 v35, 1, v33
	s_nop 0
	v_cndmask_b32_e64 v34, v33, v34, s[44:45]
	v_fma_f32 v33, -v35, v33, v32
	v_cmp_lt_f32_e64 s[44:45], 0, v33
	s_nop 1
	v_cndmask_b32_e64 v33, v34, v35, s[44:45]
	v_mul_f32_e32 v34, 0x37800000, v33
	v_cndmask_b32_e32 v33, v33, v34, vcc
	v_cmp_class_f32_e32 vcc, v32, v227
	s_nop 1
	v_cndmask_b32_e32 v32, v33, v32, vcc
	v_div_scale_f32 v33, s[0:1], v32, v32, 1.0
	v_rcp_f32_e32 v34, v33
	s_nop 0
; __device__ __forceinline__ unsigned cvtpk(float lo, float hi) { f32x2_t v = {lo, hi}; bf16x2_t b = __builtin_convertvector(v, bf16x2_t); return __builtin_bit_cast(unsigned, b); }
; __device__ __forceinline__ float ss_rs(u64 v) { return 1.f / sqrtf((float)v * (SSFI / 1024.f) + 1e-6f); }
; #define PG8_BAR __builtin_amdgcn_s_barrier()
; template <class Epi, bool ALIGN_EPI = true>
; __device__ __forceinline__ void gemm_phase(LAS unsigned char* lds, const Gemm g, const StaticOrder& S, const Epi& E, int wave_k) {
;     ...
;         if (!has_next) break;
; #pragma unroll
;         for (int a = 0; a < 2; ++a)
; #pragma unroll
;             for (int b = 0; b < 2; ++b)
; #pragma unroll
;                 for (int m = 0; m < 4; ++m)
; #pragma unroll
;                     for (int n = 0; n < 2; ++n) acc[a][b][m][n] = (f32x4){0.f, 0.f, 0.f, 0.f};
;         cur = nxt; cA = nA; cB = nB; ++ui;
;         if constexpr (ALIGN_EPI) { if (wr == 1) PG8_BAR; }
;     __device__ __forceinline__ void operator()(const Acc& acc, const Unit& u, int wr, int wc, int fr, int fq) const {
;     ...
;                 const int row = row0 + ai * HALF + m * 16; const float rs = ss_rs(sv[ai][m]);
;                 unsigned w[4];
; #pragma unroll
;                 for (int n = 0; n < 2; ++n) {
;                     const f32x4 gv = acc[ai][0][m][n] * rs, uv = acc[ai][1][m][n] * rs; float h[4];
; #pragma unroll
;                     for (int e = 0; e < 4; ++e) { const float gg = gv[e]; h[e] = gg * __builtin_amdgcn_rcpf(1.f + __builtin_amdgcn_exp2f(-1.4426950408889634f * gg)) * uv[e]; }
;                     w[2 * n] = cvtpk(h[0], h[1]); w[2 * n + 1] = cvtpk(h[2], h[3]);
;                 }
;                 *(u32x4*)(O + (size_t)row * DFF + col0) = (u32x4){w[0], w[1], w[2], w[3]};
	v_fma_f32 v35, -v33, v34, 1.0
	v_fmac_f32_e32 v34, v35, v34
	v_div_scale_f32 v35, vcc, 1.0, v32, 1.0
	v_mul_f32_e32 v36, v35, v34
	v_fma_f32 v37, -v33, v36, v35
	v_fmac_f32_e32 v36, v37, v34
	v_fma_f32 v33, -v33, v36, v35
	v_div_fmas_f32 v33, v33, v34, v36
	v_div_fixup_f32 v32, v33, v32, 1.0
	v_pk_mul_f32 v[28:29], v[28:29], v[32:33] op_sel_hi:[1,0]
	s_nop 0
	v_mul_f32_e32 v33, 0xbfb8aa3b, v28
	v_exp_f32_e32 v33, v33
	s_nop 0
	v_add_f32_e32 v33, 1.0, v33
	v_rcp_f32_e32 v34, v33
	v_mul_f32_e32 v33, 0xbfb8aa3b, v29
	v_exp_f32_e32 v33, v33
	s_nop 0
	v_add_f32_e32 v33, 1.0, v33
	v_rcp_f32_e32 v35, v33
	v_pk_mul_f32 v[24:25], v[24:25], v[32:33] op_sel_hi:[1,0]
	v_pk_mul_f32 v[26:27], v[26:27], v[32:33] op_sel_hi:[1,0]
	v_pk_mul_f32 v[20:21], v[20:21], v[32:33] op_sel_hi:[1,0]
	v_pk_mul_f32 v[28:29], v[28:29], v[34:35]
	v_pk_mul_f32 v[16:17], v[16:17], v[32:33] op_sel_hi:[1,0]
	v_pk_mul_f32 v[24:25], v[24:25], v[28:29]
	v_pk_mul_f32 v[28:29], v[30:31], v[32:33] op_sel_hi:[1,0]
	v_cvt_pk_bf16_f32 v24, v24, v25
	v_mul_f32_e32 v30, 0xbfb8aa3b, v28
	v_mul_f32_e32 v31, 0xbfb8aa3b, v29
	v_exp_f32_e32 v30, v30
	v_exp_f32_e32 v31, v31
	v_pk_mul_f32 v[18:19], v[18:19], v[32:33] op_sel_hi:[1,0]
	v_add_f32_e32 v30, 1.0, v30
	v_add_f32_e32 v31, 1.0, v31
	v_rcp_f32_e32 v30, v30
	v_rcp_f32_e32 v31, v31
	s_nop 0
	v_pk_mul_f32 v[28:29], v[28:29], v[30:31]
	s_nop 0
	v_pk_mul_f32 v[26:27], v[26:27], v[28:29]
	s_nop 0
	v_cvt_pk_bf16_f32 v25, v26, v27
	v_mul_f32_e32 v26, 0xbfb8aa3b, v20
	v_mul_f32_e32 v27, 0xbfb8aa3b, v21
	v_exp_f32_e32 v26, v26
	v_exp_f32_e32 v27, v27
	v_add_f32_e32 v26, 1.0, v26
	v_add_f32_e32 v27, 1.0, v27
	v_rcp_f32_e32 v26, v26
	v_rcp_f32_e32 v27, v27
	s_nop 0
	v_pk_mul_f32 v[20:21], v[20:21], v[26:27]
	s_nop 0
	v_pk_mul_f32 v[16:17], v[16:17], v[20:21]
	v_pk_mul_f32 v[20:21], v[22:23], v[32:33] op_sel_hi:[1,0]
	v_cvt_pk_bf16_f32 v26, v16, v17
	v_mul_f32_e32 v22, 0xbfb8aa3b, v20
	v_mul_f32_e32 v23, 0xbfb8aa3b, v21
	v_exp_f32_e32 v22, v22
	v_exp_f32_e32 v23, v23
	v_mad_i64_i32 v[16:17], s[0:1], v162, s82, v[112:113]
	v_add_f32_e32 v22, 1.0, v22
	v_add_f32_e32 v23, 1.0, v23
	v_rcp_f32_e32 v22, v22
	v_rcp_f32_e32 v23, v23
	v_lshl_add_u64 v[16:17], v[16:17], 0, v[114:115]
	v_pk_mul_f32 v[20:21], v[20:21], v[22:23]
	s_nop 0
	v_pk_mul_f32 v[18:19], v[18:19], v[20:21]
	s_nop 0
	v_cvt_pk_bf16_f32 v27, v18, v19
	global_store_dwordx4 v[16:17], v[24:27], off sc1 nt
	v_ffbh_u32_e32 v16, v139
	v_min_u32_e32 v18, 32, v16
	v_lshlrev_b64 v[16:17], v18, v[138:139]
	v_min_u32_e32 v16, 1, v16
	v_or_b32_e32 v16, v17, v16
	v_cvt_f32_u32_e32 v16, v16
	v_sub_u32_e32 v17, 32, v18
	v_ldexp_f32 v16, v16, v17
	v_fmamk_f32 v16, v16, 0x2e800000, v226
	v_cmp_gt_f32_e32 vcc, s31, v16
	v_mul_f32_e32 v17, 0x4f800000, v16
	s_nop 0
	v_cndmask_b32_e32 v16, v16, v17, vcc
	v_sqrt_f32_e32 v17, v16
	s_nop 0
	v_add_u32_e32 v18, -1, v17
	v_fma_f32 v19, -v18, v17, v16
	v_cmp_ge_f32_e64 s[44:45], 0, v19
	v_add_u32_e32 v19, 1, v17
	s_nop 0
	v_cndmask_b32_e64 v18, v17, v18, s[44:45]
	v_fma_f32 v17, -v19, v17, v16
	v_cmp_lt_f32_e64 s[44:45], 0, v17
	s_nop 1
	v_cndmask_b32_e64 v17, v18, v19, s[44:45]
	v_mul_f32_e32 v18, 0x37800000, v17
	v_cndmask_b32_e32 v17, v17, v18, vcc
	v_cmp_class_f32_e32 vcc, v16, v227
	s_nop 1
	v_cndmask_b32_e32 v16, v17, v16, vcc
	v_div_scale_f32 v17, s[0:1], v16, v16, 1.0
	v_rcp_f32_e32 v18, v17
	s_nop 0
	v_fma_f32 v19, -v17, v18, 1.0
	v_fmac_f32_e32 v18, v19, v18
	v_div_scale_f32 v19, vcc, 1.0, v16, 1.0
	v_mul_f32_e32 v20, v19, v18
	v_fma_f32 v21, -v17, v20, v19
	v_fmac_f32_e32 v20, v21, v18
	v_fma_f32 v17, -v17, v20, v19
	v_div_fmas_f32 v17, v17, v18, v20
	v_div_fixup_f32 v16, v17, v16, 1.0
	v_pk_mul_f32 v[12:13], v[12:13], v[16:17] op_sel_hi:[1,0]
	s_andn2_b64 vcc, exec, s[42:43]
	v_mul_f32_e32 v17, 0xbfb8aa3b, v12
	v_exp_f32_e32 v17, v17
	s_nop 0
	v_add_f32_e32 v17, 1.0, v17
	v_rcp_f32_e32 v18, v17
	v_mul_f32_e32 v17, 0xbfb8aa3b, v13
	v_exp_f32_e32 v17, v17
	s_nop 0
	v_add_f32_e32 v17, 1.0, v17
	v_rcp_f32_e32 v19, v17
	v_pk_mul_f32 v[8:9], v[8:9], v[16:17] op_sel_hi:[1,0]
	v_pk_mul_f32 v[10:11], v[10:11], v[16:17] op_sel_hi:[1,0]
	v_pk_mul_f32 v[4:5], v[4:5], v[16:17] op_sel_hi:[1,0]
	v_pk_mul_f32 v[12:13], v[12:13], v[18:19]
	v_pk_mul_f32 v[0:1], v[0:1], v[16:17] op_sel_hi:[1,0]
	v_pk_mul_f32 v[8:9], v[8:9], v[12:13]
	v_pk_mul_f32 v[12:13], v[14:15], v[16:17] op_sel_hi:[1,0]
	v_cvt_pk_bf16_f32 v8, v8, v9
	v_mul_f32_e32 v14, 0xbfb8aa3b, v12
	v_mul_f32_e32 v15, 0xbfb8aa3b, v13
	v_exp_f32_e32 v14, v14
	v_exp_f32_e32 v15, v15
	v_pk_mul_f32 v[2:3], v[2:3], v[16:17] op_sel_hi:[1,0]
	v_add_f32_e32 v14, 1.0, v14
	v_add_f32_e32 v15, 1.0, v15
	v_rcp_f32_e32 v14, v14
	v_rcp_f32_e32 v15, v15
	s_nop 0
	v_pk_mul_f32 v[12:13], v[12:13], v[14:15]
	s_nop 0
	v_pk_mul_f32 v[10:11], v[10:11], v[12:13]
	s_nop 0
	v_cvt_pk_bf16_f32 v9, v10, v11
	v_mul_f32_e32 v10, 0xbfb8aa3b, v4
	v_mul_f32_e32 v11, 0xbfb8aa3b, v5
	v_exp_f32_e32 v10, v10
	v_exp_f32_e32 v11, v11
	v_add_f32_e32 v10, 1.0, v10
	v_add_f32_e32 v11, 1.0, v11
	v_rcp_f32_e32 v10, v10
	v_rcp_f32_e32 v11, v11
	s_nop 0
	v_pk_mul_f32 v[4:5], v[4:5], v[10:11]
	s_nop 0
	v_pk_mul_f32 v[0:1], v[0:1], v[4:5]
	v_pk_mul_f32 v[4:5], v[6:7], v[16:17] op_sel_hi:[1,0]
	v_cvt_pk_bf16_f32 v10, v0, v1
	v_mul_f32_e32 v6, 0xbfb8aa3b, v4
	v_mul_f32_e32 v7, 0xbfb8aa3b, v5
	v_exp_f32_e32 v6, v6
	v_exp_f32_e32 v7, v7
	v_mad_i64_i32 v[0:1], s[0:1], v153, s82, v[112:113]
	v_add_f32_e32 v6, 1.0, v6
	v_add_f32_e32 v7, 1.0, v7
	v_rcp_f32_e32 v6, v6
	v_rcp_f32_e32 v7, v7
	v_lshl_add_u64 v[0:1], v[0:1], 0, v[114:115]
	s_mov_b64 s[0:1], -1
	v_pk_mul_f32 v[4:5], v[4:5], v[6:7]
	s_nop 0
	v_pk_mul_f32 v[2:3], v[2:3], v[4:5]
	s_nop 0
	v_cvt_pk_bf16_f32 v11, v2, v3
	global_store_dwordx4 v[0:1], v[8:11], off sc1 nt
	s_cbranch_vccnz .LBB0_1137
	s_andn2_b64 vcc, exec, s[14:15]
	s_cbranch_vccnz .LBB0_1136
	s_barrier
	s_branch .LBB0_1136
